# P1 input-projection epilogue: bf16 outputs stored write-through (sc1); f32 k/v rows stay plain
# speedup vs baseline: 1.0212x; 1.0212x over previous
.LBB0_96:
	s_mov_b64 s[0:1], 0x2c000
	v_lshl_add_u64 v[4:5], v[24:25], 0, s[0:1]
	v_cvt_pk_bf16_f32 v0, v8, v9
	v_cvt_pk_bf16_f32 v1, v10, v11
	v_cvt_pk_bf16_f32 v2, v12, v13
	v_cvt_pk_bf16_f32 v3, v14, v15
	global_store_dwordx4 v[4:5], v[0:3], off offset:256 sc1

.LBB0_101:
	ds_read_b128 v[128:131], v170
	ds_read_b128 v[132:135], v170 offset:1024
	ds_read_b128 v[162:165], v170 offset:2048
	ds_read_b128 v[166:169], v170 offset:3072
	ds_read_b128 v[174:177], v171
	ds_read_b128 v[178:181], v171 offset:1024
	ds_read_b128 v[182:185], v171 offset:2048
	ds_read_b128 v[186:189], v171 offset:3072
	s_add_u32 s6, s4, 0xfffc0080
	s_addc_u32 s7, s5, -1
	s_cmp_eq_u32 s21, 12
	s_cselect_b32 s19, s0, s7
	s_cselect_b32 s18, s1, s6
	s_cselect_b32 s7, s3, s20
	s_cselect_b32 s6, s14, s17
	v_lshl_add_u64 v[222:223], s[4:5], 0, v[154:155]
	s_add_i32 m0, s50, 0xc000
	ds_read_b128 v[190:193], v172
	ds_read_b128 v[194:197], v172 offset:1024
	ds_read_b128 v[198:201], v172 offset:2048
	ds_read_b128 v[202:205], v172 offset:3072
	ds_read_b128 v[206:209], v172 offset:4096
	ds_read_b128 v[210:213], v172 offset:5120
	ds_read_b128 v[214:217], v172 offset:6144
	ds_read_b128 v[218:221], v172 offset:7168
	global_load_lds_dwordx4 v[222:223], off
	v_lshl_add_u64 v[222:223], s[4:5], 0, v[156:157]
	s_add_i32 m0, s50, 0xe000
	s_nop 0
	global_load_lds_dwordx4 v[222:223], off
	s_waitcnt vmcnt(8)
	s_waitcnt lgkmcnt(0)
	s_barrier
	s_setprio 1
	s_waitcnt lgkmcnt(0)
	v_mfma_f32_16x16x32_bf16 v[124:127], v[128:131], v[190:193], v[124:127]
	v_mfma_f32_16x16x32_bf16 v[120:123], v[162:165], v[190:193], v[120:123]
	v_mfma_f32_16x16x32_bf16 v[108:111], v[128:131], v[198:201], v[108:111]
	v_mfma_f32_16x16x32_bf16 v[104:107], v[162:165], v[198:201], v[104:107]
	v_mfma_f32_16x16x32_bf16 v[92:95], v[128:131], v[206:209], v[92:95]
	v_mfma_f32_16x16x32_bf16 v[88:91], v[162:165], v[206:209], v[88:91]
	v_mfma_f32_16x16x32_bf16 v[76:79], v[128:131], v[214:217], v[76:79]
	v_mfma_f32_16x16x32_bf16 v[72:75], v[162:165], v[214:217], v[72:75]
	v_mfma_f32_16x16x32_bf16 v[124:127], v[132:135], v[194:197], v[124:127]
	v_mfma_f32_16x16x32_bf16 v[120:123], v[166:169], v[194:197], v[120:123]
	v_mfma_f32_16x16x32_bf16 v[108:111], v[132:135], v[202:205], v[108:111]
	v_mfma_f32_16x16x32_bf16 v[104:107], v[166:169], v[202:205], v[104:107]
	v_mfma_f32_16x16x32_bf16 v[92:95], v[132:135], v[210:213], v[92:95]
	v_mfma_f32_16x16x32_bf16 v[88:91], v[166:169], v[210:213], v[88:91]
	v_mfma_f32_16x16x32_bf16 v[76:79], v[132:135], v[218:221], v[76:79]
	v_mfma_f32_16x16x32_bf16 v[72:75], v[166:169], v[218:221], v[72:75]
	s_setprio 0
	s_setprio 1
	v_mfma_f32_16x16x32_bf16 v[116:119], v[174:177], v[190:193], v[116:119]
	v_mfma_f32_16x16x32_bf16 v[112:115], v[182:185], v[190:193], v[112:115]
	v_mfma_f32_16x16x32_bf16 v[100:103], v[174:177], v[198:201], v[100:103]
	v_mfma_f32_16x16x32_bf16 v[96:99], v[182:185], v[198:201], v[96:99]
	v_mfma_f32_16x16x32_bf16 v[84:87], v[174:177], v[206:209], v[84:87]
	v_mfma_f32_16x16x32_bf16 v[80:83], v[182:185], v[206:209], v[80:83]
	v_mfma_f32_16x16x32_bf16 v[68:71], v[174:177], v[214:217], v[68:71]
	v_mfma_f32_16x16x32_bf16 v[64:67], v[182:185], v[214:217], v[64:67]
	v_mfma_f32_16x16x32_bf16 v[116:119], v[178:181], v[194:197], v[116:119]
	v_mfma_f32_16x16x32_bf16 v[112:115], v[186:189], v[194:197], v[112:115]
	v_mfma_f32_16x16x32_bf16 v[100:103], v[178:181], v[202:205], v[100:103]
	v_mfma_f32_16x16x32_bf16 v[96:99], v[186:189], v[202:205], v[96:99]
	v_mfma_f32_16x16x32_bf16 v[84:87], v[178:181], v[210:213], v[84:87]
	v_mfma_f32_16x16x32_bf16 v[80:83], v[186:189], v[210:213], v[80:83]
	v_mfma_f32_16x16x32_bf16 v[68:71], v[178:181], v[218:221], v[68:71]
	v_mfma_f32_16x16x32_bf16 v[64:67], v[186:189], v[218:221], v[64:67]
	s_setprio 0
	s_barrier
	s_add_i32 s24, s95, s23
	v_lshl_add_u64 v[222:223], s[6:7], 0, v[138:139]
	s_mov_b32 m0, s24
	ds_read_b128 v[190:193], v172 offset:16384
	ds_read_b128 v[194:197], v172 offset:17408
	ds_read_b128 v[198:201], v172 offset:18432
	ds_read_b128 v[202:205], v172 offset:19456
	ds_read_b128 v[206:209], v172 offset:20480
	ds_read_b128 v[210:213], v172 offset:21504
	ds_read_b128 v[214:217], v172 offset:22528
	ds_read_b128 v[218:221], v172 offset:23552
	global_load_lds_dwordx4 v[222:223], off
	s_add_i32 m0, s24, 0x2000
	s_add_u32 s28, s6, 0x40000
	v_lshl_add_u64 v[224:225], s[6:7], 0, v[142:143]
	s_addc_u32 s29, s7, 0
	s_add_i32 s24, s96, s23
	global_load_lds_dwordx4 v[224:225], off
	v_lshl_add_u64 v[226:227], s[28:29], 0, v[138:139]
	s_mov_b32 m0, s24
	v_lshl_add_u64 v[228:229], s[18:19], 0, v[140:141]
	global_load_lds_dwordx4 v[226:227], off
	v_lshl_add_u64 v[226:227], s[28:29], 0, v[142:143]
	s_add_i32 m0, s24, 0x2000
	s_nop 0
	global_load_lds_dwordx4 v[226:227], off
	v_lshl_add_u64 v[226:227], s[18:19], 0, v[136:137]
	s_mov_b32 m0, s50
	s_nop 0
	global_load_lds_dwordx4 v[226:227], off
	s_mov_b32 m0, s51
	s_nop 0
	global_load_lds_dwordx4 v[228:229], off
	s_waitcnt vmcnt(8)
	s_waitcnt lgkmcnt(0)
	s_barrier
	s_setprio 1
	s_waitcnt lgkmcnt(0)
	v_mfma_f32_16x16x32_bf16 v[60:63], v[128:131], v[190:193], v[60:63]
	v_mfma_f32_16x16x32_bf16 v[56:59], v[162:165], v[190:193], v[56:59]
	v_mfma_f32_16x16x32_bf16 v[44:47], v[128:131], v[198:201], v[44:47]
	v_mfma_f32_16x16x32_bf16 v[40:43], v[162:165], v[198:201], v[40:43]
	v_mfma_f32_16x16x32_bf16 v[28:31], v[128:131], v[206:209], v[28:31]
	v_mfma_f32_16x16x32_bf16 v[24:27], v[162:165], v[206:209], v[24:27]
	v_mfma_f32_16x16x32_bf16 v[12:15], v[128:131], v[214:217], v[12:15]
	v_mfma_f32_16x16x32_bf16 v[8:11], v[162:165], v[214:217], v[8:11]
	v_mfma_f32_16x16x32_bf16 v[60:63], v[132:135], v[194:197], v[60:63]
	v_mfma_f32_16x16x32_bf16 v[56:59], v[166:169], v[194:197], v[56:59]
	v_mfma_f32_16x16x32_bf16 v[44:47], v[132:135], v[202:205], v[44:47]
	v_mfma_f32_16x16x32_bf16 v[40:43], v[166:169], v[202:205], v[40:43]
	v_mfma_f32_16x16x32_bf16 v[28:31], v[132:135], v[210:213], v[28:31]
	v_mfma_f32_16x16x32_bf16 v[24:27], v[166:169], v[210:213], v[24:27]
	v_mfma_f32_16x16x32_bf16 v[12:15], v[132:135], v[218:221], v[12:15]
	v_mfma_f32_16x16x32_bf16 v[8:11], v[166:169], v[218:221], v[8:11]
	s_setprio 0
	s_setprio 1
	v_mfma_f32_16x16x32_bf16 v[52:55], v[174:177], v[190:193], v[52:55]
	v_mfma_f32_16x16x32_bf16 v[48:51], v[182:185], v[190:193], v[48:51]
	v_mfma_f32_16x16x32_bf16 v[36:39], v[174:177], v[198:201], v[36:39]
	v_mfma_f32_16x16x32_bf16 v[32:35], v[182:185], v[198:201], v[32:35]
	v_mfma_f32_16x16x32_bf16 v[20:23], v[174:177], v[206:209], v[20:23]
	v_mfma_f32_16x16x32_bf16 v[16:19], v[182:185], v[206:209], v[16:19]
	v_mfma_f32_16x16x32_bf16 v[4:7], v[174:177], v[214:217], v[4:7]
	v_mfma_f32_16x16x32_bf16 v[0:3], v[182:185], v[214:217], v[0:3]
	v_mfma_f32_16x16x32_bf16 v[52:55], v[178:181], v[194:197], v[52:55]
	v_mfma_f32_16x16x32_bf16 v[48:51], v[186:189], v[194:197], v[48:51]
	v_mfma_f32_16x16x32_bf16 v[36:39], v[178:181], v[202:205], v[36:39]
	v_mfma_f32_16x16x32_bf16 v[32:35], v[186:189], v[202:205], v[32:35]
	v_mfma_f32_16x16x32_bf16 v[20:23], v[178:181], v[210:213], v[20:23]
	v_mfma_f32_16x16x32_bf16 v[16:19], v[186:189], v[210:213], v[16:19]
	v_mfma_f32_16x16x32_bf16 v[4:7], v[178:181], v[218:221], v[4:7]
	v_mfma_f32_16x16x32_bf16 v[0:3], v[186:189], v[218:221], v[0:3]
	s_setprio 0
	s_barrier
	s_add_i32 s24, 0, 0x18000
	v_add_u32_e32 v144, s24, v149
	s_add_i32 s26, 0, 0x1c000
	ds_read_b128 v[128:131], v144
	ds_read_b128 v[132:135], v144 offset:1024
	ds_read_b128 v[162:165], v144 offset:2048
	ds_read_b128 v[166:169], v144 offset:3072
	v_add_u32_e32 v144, s26, v149
	ds_read_b128 v[174:177], v144
	ds_read_b128 v[178:181], v144 offset:1024
	ds_read_b128 v[182:185], v144 offset:2048
	ds_read_b128 v[186:189], v144 offset:3072
	s_add_u32 s18, s18, 0x40000
	s_addc_u32 s19, s19, 0
	s_mov_b32 m0, s71
	v_lshl_add_u64 v[230:231], s[18:19], 0, v[136:137]
	ds_read_b128 v[190:193], v172 offset:32768
	ds_read_b128 v[194:197], v172 offset:33792
	ds_read_b128 v[198:201], v172 offset:34816
	ds_read_b128 v[202:205], v172 offset:35840
	ds_read_b128 v[206:209], v172 offset:36864
	ds_read_b128 v[210:213], v172 offset:37888
	ds_read_b128 v[214:217], v172 offset:38912
	ds_read_b128 v[218:221], v172 offset:39936
	global_load_lds_dwordx4 v[230:231], off
	v_lshl_add_u64 v[230:231], s[18:19], 0, v[140:141]
	s_mov_b32 m0, s80
	s_nop 0
	global_load_lds_dwordx4 v[230:231], off
	s_waitcnt vmcnt(8)
	s_waitcnt lgkmcnt(0)
	s_barrier
	s_setprio 1
	s_waitcnt lgkmcnt(0)
	v_mfma_f32_16x16x32_bf16 v[124:127], v[128:131], v[190:193], v[124:127]
	v_mfma_f32_16x16x32_bf16 v[120:123], v[162:165], v[190:193], v[120:123]
	v_mfma_f32_16x16x32_bf16 v[108:111], v[128:131], v[198:201], v[108:111]
	v_mfma_f32_16x16x32_bf16 v[104:107], v[162:165], v[198:201], v[104:107]
	v_mfma_f32_16x16x32_bf16 v[92:95], v[128:131], v[206:209], v[92:95]
	v_mfma_f32_16x16x32_bf16 v[88:91], v[162:165], v[206:209], v[88:91]
	v_mfma_f32_16x16x32_bf16 v[76:79], v[128:131], v[214:217], v[76:79]
	v_mfma_f32_16x16x32_bf16 v[72:75], v[162:165], v[214:217], v[72:75]
	v_mfma_f32_16x16x32_bf16 v[124:127], v[132:135], v[194:197], v[124:127]
	v_mfma_f32_16x16x32_bf16 v[120:123], v[166:169], v[194:197], v[120:123]
	v_mfma_f32_16x16x32_bf16 v[108:111], v[132:135], v[202:205], v[108:111]
	v_mfma_f32_16x16x32_bf16 v[104:107], v[166:169], v[202:205], v[104:107]
	v_mfma_f32_16x16x32_bf16 v[92:95], v[132:135], v[210:213], v[92:95]
	v_mfma_f32_16x16x32_bf16 v[88:91], v[166:169], v[210:213], v[88:91]
	v_mfma_f32_16x16x32_bf16 v[76:79], v[132:135], v[218:221], v[76:79]
	v_mfma_f32_16x16x32_bf16 v[72:75], v[166:169], v[218:221], v[72:75]
	s_setprio 0
	s_setprio 1
	v_mfma_f32_16x16x32_bf16 v[116:119], v[174:177], v[190:193], v[116:119]
	v_mfma_f32_16x16x32_bf16 v[112:115], v[182:185], v[190:193], v[112:115]
	v_mfma_f32_16x16x32_bf16 v[100:103], v[174:177], v[198:201], v[100:103]
	v_mfma_f32_16x16x32_bf16 v[96:99], v[182:185], v[198:201], v[96:99]
	v_mfma_f32_16x16x32_bf16 v[84:87], v[174:177], v[206:209], v[84:87]
	v_mfma_f32_16x16x32_bf16 v[80:83], v[182:185], v[206:209], v[80:83]
	v_mfma_f32_16x16x32_bf16 v[68:71], v[174:177], v[214:217], v[68:71]
	v_mfma_f32_16x16x32_bf16 v[64:67], v[182:185], v[214:217], v[64:67]
	v_mfma_f32_16x16x32_bf16 v[116:119], v[178:181], v[194:197], v[116:119]
	v_mfma_f32_16x16x32_bf16 v[112:115], v[186:189], v[194:197], v[112:115]
	v_mfma_f32_16x16x32_bf16 v[100:103], v[178:181], v[202:205], v[100:103]
	v_mfma_f32_16x16x32_bf16 v[96:99], v[186:189], v[202:205], v[96:99]
	v_mfma_f32_16x16x32_bf16 v[84:87], v[178:181], v[210:213], v[84:87]
	v_mfma_f32_16x16x32_bf16 v[80:83], v[186:189], v[210:213], v[80:83]
	v_mfma_f32_16x16x32_bf16 v[68:71], v[178:181], v[218:221], v[68:71]
	v_mfma_f32_16x16x32_bf16 v[64:67], v[186:189], v[218:221], v[64:67]
	s_setprio 0
	s_barrier
	s_add_i32 s18, s24, s23
	v_lshl_add_u64 v[222:223], v[222:223], 0, s[30:31]
	s_mov_b32 m0, s18
	ds_read_b128 v[190:193], v172 offset:49152
	ds_read_b128 v[194:197], v172 offset:50176
	ds_read_b128 v[198:201], v172 offset:51200
	ds_read_b128 v[202:205], v172 offset:52224
	ds_read_b128 v[206:209], v172 offset:53248
	ds_read_b128 v[210:213], v172 offset:54272
	ds_read_b128 v[214:217], v172 offset:55296
	ds_read_b128 v[218:221], v172 offset:56320
	global_load_lds_dwordx4 v[222:223], off
	s_add_i32 m0, s18, 0x2000
	s_add_u32 s6, s6, 0x40080
	v_lshl_add_u64 v[222:223], v[224:225], 0, s[30:31]
	s_addc_u32 s7, s7, 0
	s_add_i32 s18, s26, s23
	global_load_lds_dwordx4 v[222:223], off
	v_lshl_add_u64 v[222:223], s[6:7], 0, v[138:139]
	s_mov_b32 m0, s18
	s_nop 0
	global_load_lds_dwordx4 v[222:223], off
	v_lshl_add_u64 v[222:223], s[6:7], 0, v[142:143]
	s_add_i32 m0, s18, 0x2000
	s_nop 0
	global_load_lds_dwordx4 v[222:223], off
	v_lshl_add_u64 v[222:223], v[226:227], 0, s[30:31]
	s_mov_b32 m0, s91
	s_nop 0
	global_load_lds_dwordx4 v[222:223], off
	v_lshl_add_u64 v[222:223], v[228:229], 0, s[30:31]
	s_mov_b32 m0, s92
	s_nop 0
	global_load_lds_dwordx4 v[222:223], off
	s_waitcnt vmcnt(8)
	s_waitcnt lgkmcnt(0)
	s_barrier
	s_setprio 1
	s_waitcnt lgkmcnt(0)
	v_mfma_f32_16x16x32_bf16 v[60:63], v[128:131], v[190:193], v[60:63]
	v_mfma_f32_16x16x32_bf16 v[56:59], v[162:165], v[190:193], v[56:59]
	v_mfma_f32_16x16x32_bf16 v[44:47], v[128:131], v[198:201], v[44:47]
	v_mfma_f32_16x16x32_bf16 v[40:43], v[162:165], v[198:201], v[40:43]
	v_mfma_f32_16x16x32_bf16 v[28:31], v[128:131], v[206:209], v[28:31]
	v_mfma_f32_16x16x32_bf16 v[24:27], v[162:165], v[206:209], v[24:27]
	v_mfma_f32_16x16x32_bf16 v[12:15], v[128:131], v[214:217], v[12:15]
	v_mfma_f32_16x16x32_bf16 v[8:11], v[162:165], v[214:217], v[8:11]
	v_mfma_f32_16x16x32_bf16 v[60:63], v[132:135], v[194:197], v[60:63]
	v_mfma_f32_16x16x32_bf16 v[56:59], v[166:169], v[194:197], v[56:59]
	v_mfma_f32_16x16x32_bf16 v[44:47], v[132:135], v[202:205], v[44:47]
	v_mfma_f32_16x16x32_bf16 v[40:43], v[166:169], v[202:205], v[40:43]
	v_mfma_f32_16x16x32_bf16 v[28:31], v[132:135], v[210:213], v[28:31]
	v_mfma_f32_16x16x32_bf16 v[24:27], v[166:169], v[210:213], v[24:27]
	v_mfma_f32_16x16x32_bf16 v[12:15], v[132:135], v[218:221], v[12:15]
	v_mfma_f32_16x16x32_bf16 v[8:11], v[166:169], v[218:221], v[8:11]
	s_setprio 0
	s_setprio 1
	v_mfma_f32_16x16x32_bf16 v[52:55], v[174:177], v[190:193], v[52:55]
	v_mfma_f32_16x16x32_bf16 v[48:51], v[182:185], v[190:193], v[48:51]
	v_mfma_f32_16x16x32_bf16 v[36:39], v[174:177], v[198:201], v[36:39]
	v_mfma_f32_16x16x32_bf16 v[32:35], v[182:185], v[198:201], v[32:35]
	v_mfma_f32_16x16x32_bf16 v[20:23], v[174:177], v[206:209], v[20:23]
	v_mfma_f32_16x16x32_bf16 v[16:19], v[182:185], v[206:209], v[16:19]
	v_mfma_f32_16x16x32_bf16 v[4:7], v[174:177], v[214:217], v[4:7]
	v_mfma_f32_16x16x32_bf16 v[0:3], v[182:185], v[214:217], v[0:3]
	v_mfma_f32_16x16x32_bf16 v[52:55], v[178:181], v[194:197], v[52:55]
	v_mfma_f32_16x16x32_bf16 v[48:51], v[186:189], v[194:197], v[48:51]
	v_mfma_f32_16x16x32_bf16 v[36:39], v[178:181], v[202:205], v[36:39]
	v_mfma_f32_16x16x32_bf16 v[32:35], v[186:189], v[202:205], v[32:35]
	v_mfma_f32_16x16x32_bf16 v[20:23], v[178:181], v[210:213], v[20:23]
	v_mfma_f32_16x16x32_bf16 v[16:19], v[186:189], v[210:213], v[16:19]
	v_mfma_f32_16x16x32_bf16 v[4:7], v[178:181], v[218:221], v[4:7]
	v_mfma_f32_16x16x32_bf16 v[0:3], v[186:189], v[218:221], v[0:3]
	s_setprio 0
	s_barrier
	s_add_i32 s21, s21, 2
	s_add_u32 s4, s4, 0x100
	s_addc_u32 s5, s5, 0
	s_add_u32 s17, s17, 0x100
	s_addc_u32 s20, s20, 0
	s_cmp_gt_u32 s21, 13
	s_cbranch_scc0 .LBB0_101
	s_lshl_b32 s0, s16, 8
	s_add_i32 s0, s0, s81
	s_and_b32 s1, s2, -2
	s_cmp_lg_u32 s1, 6
	s_cselect_b64 s[4:5], -1, 0
	s_add_i32 s1, s2, -12
	s_cmp_gt_u32 s1, -11
	s_cselect_b64 s[6:7], -1, 0
	s_and_b64 s[6:7], s[6:7], s[4:5]
	v_or_b32_e32 v162, s0, v147
	s_mov_b64 s[4:5], -1
	s_and_b64 vcc, exec, s[6:7]
	s_cbranch_vccz .LBB0_188
	s_cmp_gt_u32 s2, 5
	s_cbranch_scc0 .LBB0_185
	v_cmp_lt_i32_e64 s[6:7], s97, v162
	s_and_saveexec_b64 s[4:5], s[6:7]
	s_xor_b64 s[4:5], exec, s[4:5]
	v_add_u32_e32 v128, 0xffffc000, v162
	v_lshrrev_b32_e32 v128, 3, v128
	v_mad_u64_u32 v[166:167], s[18:19], v128, 38, v[148:149]
	s_or_saveexec_b64 s[4:5], s[4:5]
	s_ashr_i32 s0, s0, 13
	s_mul_i32 s18, s0, 30
	s_add_i32 s1, s18, 30
	s_xor_b64 exec, exec, s[4:5]
	v_add_u32_e32 v166, s1, v162
	s_or_b64 exec, exec, s[4:5]
	v_mul_f32_e32 v132, 0xbfb8aa3b, v112
	v_exp_f32_e32 v132, v132
	v_mul_f32_e32 v133, 0xbfb8aa3b, v113
	v_exp_f32_e32 v133, v133
	v_mul_f32_e32 v128, 0xbfb8aa3b, v116
	v_add_f32_e32 v132, 1.0, v132
	v_rcp_f32_e32 v168, v132
	v_add_f32_e32 v132, 1.0, v133
	v_mul_f32_e32 v133, 0xbfb8aa3b, v114
	v_mul_f32_e32 v129, 0xbfb8aa3b, v117
	v_mul_f32_e32 v130, 0xbfb8aa3b, v118
	v_mul_f32_e32 v131, 0xbfb8aa3b, v119
	v_exp_f32_e32 v133, v133
	v_mul_f32_e32 v134, 0xbfb8aa3b, v115
	v_exp_f32_e32 v128, v128
	v_exp_f32_e32 v129, v129
	v_exp_f32_e32 v130, v130
	v_exp_f32_e32 v131, v131
	v_exp_f32_e32 v134, v134
	s_lshl_b32 s0, s2, 7
	s_lshl_b32 s14, s2, 8
	s_and_b32 s3, s16, 31
	v_rcp_f32_e32 v169, v132
	v_add_f32_e32 v132, 1.0, v133
	s_cmp_eq_u32 s3, 31
	v_add_f32_e32 v128, 1.0, v128
	v_add_f32_e32 v129, 1.0, v129
	v_add_f32_e32 v130, 1.0, v130
	v_add_f32_e32 v131, 1.0, v131
	v_rcp_f32_e32 v174, v132
	v_add_f32_e32 v132, 1.0, v134
	s_cselect_b64 s[4:5], -1, 0
	s_cmp_gt_i32 s16, 63
	v_rcp_f32_e32 v128, v128
	v_rcp_f32_e32 v129, v129
	v_rcp_f32_e32 v130, v130
	v_rcp_f32_e32 v131, v131
	v_rcp_f32_e32 v175, v132
	s_cselect_b64 s[20:21], -1, 0
	v_ashrrev_i32_e32 v167, 31, v166
	s_or_b64 s[20:21], s[20:21], s[4:5]
	v_lshl_add_u64 v[164:165], v[152:153], 0, s[14:15]
	v_lshlrev_b64 v[166:167], 10, v[166:167]
	v_cndmask_b32_e64 v144, 0, 1, s[20:21]
	v_pk_mul_f32 v[132:133], v[124:125], v[128:129]
	v_pk_mul_f32 v[134:135], v[126:127], v[130:131]
	v_pk_mul_f32 v[128:129], v[120:121], v[168:169]
	v_pk_mul_f32 v[130:131], v[122:123], v[174:175]
	v_lshl_add_u64 v[166:167], v[164:165], 0, v[166:167]
	v_cmp_ne_u32_e64 s[4:5], 1, v144
	s_andn2_b64 vcc, exec, s[20:21]
	v_cvt_pk_bf16_f32 v174, v132, v133
	v_cvt_pk_bf16_f32 v175, v134, v135
	v_cvt_pk_bf16_f32 v176, v128, v129
	v_cvt_pk_bf16_f32 v177, v130, v131
	global_store_dwordx4 v[166:167], v[174:177], off offset:-2048 sc1
	s_cbranch_vccnz .LBB0_114
	v_mov_b64_e32 v[166:167], -1
	s_and_saveexec_b64 s[20:21], s[6:7]
	v_add_u32_e32 v144, 0xffffc000, v162
	v_lshrrev_b32_e32 v144, 3, v144
	v_mad_u64_u32 v[166:167], s[6:7], v144, 30, v[150:151]
	v_lshlrev_b64 v[166:167], 9, v[166:167]
	v_lshl_add_u64 v[166:167], v[166:167], 0, s[34:35]
	s_or_b64 exec, exec, s[20:21]
	v_cmp_lt_i64_e32 vcc, -1, v[166:167]
	s_and_saveexec_b64 s[6:7], vcc
	s_cbranch_execz .LBB0_113
	v_readlane_b32 s84, v247, 20
	v_readlane_b32 s86, v247, 22
	v_readlane_b32 s87, v247, 23
	v_add_u32_e32 v144, s0, v146
	v_readlane_b32 s85, v247, 21
	v_lshl_add_u64 v[166:167], v[166:167], 2, s[86:87]
	v_lshl_add_u64 v[166:167], v[144:145], 2, v[166:167]
	global_store_dwordx4 v[166:167], v[132:135], off offset:-4096
	global_store_dwordx4 v[166:167], v[128:131], off offset:-4080

.LBB0_114:
	s_nop 0
	v_or_b32_e32 v128, 16, v162
	v_cmp_lt_i32_e64 s[6:7], s97, v128
	s_and_saveexec_b64 s[20:21], s[6:7]
	s_xor_b64 s[20:21], exec, s[20:21]
	v_add_u32_e32 v128, 0xffffc010, v162
	v_lshrrev_b32_e32 v128, 3, v128
	v_mad_u64_u32 v[166:167], s[28:29], v128, 38, v[148:149]
	s_andn2_saveexec_b64 s[20:21], s[20:21]
	v_add_u32_e32 v166, s1, v128
	s_or_b64 exec, exec, s[20:21]
	v_mul_f32_e32 v132, 0xbfb8aa3b, v96
	v_exp_f32_e32 v132, v132
	v_mul_f32_e32 v133, 0xbfb8aa3b, v97
	v_exp_f32_e32 v133, v133
	v_mul_f32_e32 v128, 0xbfb8aa3b, v100
	v_add_f32_e32 v132, 1.0, v132
	v_rcp_f32_e32 v168, v132
	v_add_f32_e32 v132, 1.0, v133
	v_mul_f32_e32 v133, 0xbfb8aa3b, v98
	v_mul_f32_e32 v129, 0xbfb8aa3b, v101
	v_mul_f32_e32 v130, 0xbfb8aa3b, v102
	v_mul_f32_e32 v131, 0xbfb8aa3b, v103
	v_exp_f32_e32 v133, v133
	v_mul_f32_e32 v134, 0xbfb8aa3b, v99
	v_exp_f32_e32 v128, v128
	v_exp_f32_e32 v129, v129
	v_exp_f32_e32 v130, v130
	v_exp_f32_e32 v131, v131
	v_exp_f32_e32 v134, v134
	v_rcp_f32_e32 v169, v132
	v_add_f32_e32 v132, 1.0, v133
	v_add_f32_e32 v128, 1.0, v128
	v_add_f32_e32 v129, 1.0, v129
	v_add_f32_e32 v130, 1.0, v130
	v_add_f32_e32 v131, 1.0, v131
	v_rcp_f32_e32 v174, v132
	v_add_f32_e32 v132, 1.0, v134
	v_rcp_f32_e32 v128, v128
	v_rcp_f32_e32 v129, v129
	v_rcp_f32_e32 v130, v130
	v_rcp_f32_e32 v131, v131
	v_rcp_f32_e32 v175, v132
	v_ashrrev_i32_e32 v167, 31, v166
	v_lshlrev_b64 v[166:167], 10, v[166:167]
	v_pk_mul_f32 v[132:133], v[108:109], v[128:129]
	v_pk_mul_f32 v[134:135], v[110:111], v[130:131]
	v_pk_mul_f32 v[128:129], v[104:105], v[168:169]
	v_pk_mul_f32 v[130:131], v[106:107], v[174:175]
	v_lshl_add_u64 v[166:167], v[164:165], 0, v[166:167]
	s_and_b64 vcc, exec, s[4:5]
	v_cvt_pk_bf16_f32 v174, v132, v133
	v_cvt_pk_bf16_f32 v175, v134, v135
	v_cvt_pk_bf16_f32 v176, v128, v129
	v_cvt_pk_bf16_f32 v177, v130, v131
	global_store_dwordx4 v[166:167], v[174:177], off offset:-2048 sc1
	s_cbranch_vccnz .LBB0_124
	v_mov_b64_e32 v[166:167], -1
	s_and_saveexec_b64 s[20:21], s[6:7]
	v_add_u32_e32 v144, 0xffffc010, v162
	v_lshrrev_b32_e32 v144, 3, v144
	v_mad_u64_u32 v[166:167], s[6:7], v144, 30, v[150:151]
	v_lshlrev_b64 v[166:167], 9, v[166:167]
	v_lshl_add_u64 v[166:167], v[166:167], 0, s[34:35]
	s_or_b64 exec, exec, s[20:21]
	v_cmp_lt_i64_e32 vcc, -1, v[166:167]
	s_and_saveexec_b64 s[6:7], vcc
	s_cbranch_execz .LBB0_123
	v_readlane_b32 s84, v247, 20
	v_readlane_b32 s86, v247, 22
	v_readlane_b32 s87, v247, 23
	v_add_u32_e32 v144, s0, v146
	v_readlane_b32 s85, v247, 21
	v_lshl_add_u64 v[166:167], v[166:167], 2, s[86:87]
	v_lshl_add_u64 v[166:167], v[144:145], 2, v[166:167]
	global_store_dwordx4 v[166:167], v[132:135], off offset:-4096
	global_store_dwordx4 v[166:167], v[128:131], off offset:-4080

.LBB0_124:
	v_or_b32_e32 v144, 32, v162
	v_cmp_lt_i32_e64 s[6:7], s97, v144
	s_and_saveexec_b64 s[20:21], s[6:7]
	s_xor_b64 s[20:21], exec, s[20:21]
	v_add_u32_e32 v128, 0xffffc020, v162
	v_lshrrev_b32_e32 v128, 3, v128
	v_mad_u64_u32 v[166:167], s[28:29], v128, 38, v[148:149]
	s_andn2_saveexec_b64 s[20:21], s[20:21]
	v_add_u32_e32 v166, s1, v144
	s_or_b64 exec, exec, s[20:21]
	v_mul_f32_e32 v132, 0xbfb8aa3b, v80
	v_exp_f32_e32 v132, v132
	v_mul_f32_e32 v133, 0xbfb8aa3b, v81
	v_exp_f32_e32 v133, v133
	v_mul_f32_e32 v128, 0xbfb8aa3b, v84
	v_add_f32_e32 v132, 1.0, v132
	v_rcp_f32_e32 v168, v132
	v_add_f32_e32 v132, 1.0, v133
	v_mul_f32_e32 v133, 0xbfb8aa3b, v82
	v_mul_f32_e32 v129, 0xbfb8aa3b, v85
	v_mul_f32_e32 v130, 0xbfb8aa3b, v86
	v_mul_f32_e32 v131, 0xbfb8aa3b, v87
	v_exp_f32_e32 v133, v133
	v_mul_f32_e32 v134, 0xbfb8aa3b, v83
	v_exp_f32_e32 v128, v128
	v_exp_f32_e32 v129, v129
	v_exp_f32_e32 v130, v130
	v_exp_f32_e32 v131, v131
	v_exp_f32_e32 v134, v134
	v_rcp_f32_e32 v169, v132
	v_add_f32_e32 v132, 1.0, v133
	v_add_f32_e32 v128, 1.0, v128
	v_add_f32_e32 v129, 1.0, v129
	v_add_f32_e32 v130, 1.0, v130
	v_add_f32_e32 v131, 1.0, v131
	v_rcp_f32_e32 v174, v132
	v_add_f32_e32 v132, 1.0, v134
	v_rcp_f32_e32 v128, v128
	v_rcp_f32_e32 v129, v129
	v_rcp_f32_e32 v130, v130
	v_rcp_f32_e32 v131, v131
	v_rcp_f32_e32 v175, v132
	v_ashrrev_i32_e32 v167, 31, v166
	v_lshlrev_b64 v[166:167], 10, v[166:167]
	s_ashr_i32 s19, s18, 31
	v_pk_mul_f32 v[132:133], v[92:93], v[128:129]
	v_pk_mul_f32 v[134:135], v[94:95], v[130:131]
	v_pk_mul_f32 v[128:129], v[88:89], v[168:169]
	v_pk_mul_f32 v[130:131], v[90:91], v[174:175]
	v_lshl_add_u64 v[166:167], v[164:165], 0, v[166:167]
	s_and_b64 vcc, exec, s[4:5]
	v_cvt_pk_bf16_f32 v174, v132, v133
	v_cvt_pk_bf16_f32 v175, v134, v135
	v_cvt_pk_bf16_f32 v176, v128, v129
	v_cvt_pk_bf16_f32 v177, v130, v131
	global_store_dwordx4 v[166:167], v[174:177], off offset:-2048 sc1
	s_cbranch_vccnz .LBB0_134
	s_and_saveexec_b64 s[20:21], s[6:7]
	s_xor_b64 s[6:7], exec, s[20:21]
	s_cbranch_execnz .LBB0_261
	s_andn2_saveexec_b64 s[6:7], s[6:7]
	s_cbranch_execnz .LBB0_262

.LBB0_134:
	v_or_b32_e32 v144, 48, v162
	v_cmp_lt_i32_e64 s[6:7], s97, v144
	s_and_saveexec_b64 s[20:21], s[6:7]
	s_xor_b64 s[20:21], exec, s[20:21]
	v_add_u32_e32 v128, 0xffffc030, v162
	v_lshrrev_b32_e32 v128, 3, v128
	v_mad_u64_u32 v[166:167], s[28:29], v128, 38, v[148:149]
	s_andn2_saveexec_b64 s[20:21], s[20:21]
	v_add_u32_e32 v166, s1, v144
	s_or_b64 exec, exec, s[20:21]
	v_mul_f32_e32 v132, 0xbfb8aa3b, v64
	v_exp_f32_e32 v132, v132
	v_mul_f32_e32 v133, 0xbfb8aa3b, v65
	v_exp_f32_e32 v133, v133
	v_mul_f32_e32 v128, 0xbfb8aa3b, v68
	v_add_f32_e32 v132, 1.0, v132
	v_rcp_f32_e32 v168, v132
	v_add_f32_e32 v132, 1.0, v133
	v_mul_f32_e32 v133, 0xbfb8aa3b, v66
	v_mul_f32_e32 v129, 0xbfb8aa3b, v69
	v_mul_f32_e32 v130, 0xbfb8aa3b, v70
	v_mul_f32_e32 v131, 0xbfb8aa3b, v71
	v_exp_f32_e32 v133, v133
	v_mul_f32_e32 v134, 0xbfb8aa3b, v67
	v_exp_f32_e32 v128, v128
	v_exp_f32_e32 v129, v129
	v_exp_f32_e32 v130, v130
	v_exp_f32_e32 v131, v131
	v_exp_f32_e32 v134, v134
	v_rcp_f32_e32 v169, v132
	v_add_f32_e32 v132, 1.0, v133
	v_add_f32_e32 v128, 1.0, v128
	v_add_f32_e32 v129, 1.0, v129
	v_add_f32_e32 v130, 1.0, v130
	v_add_f32_e32 v131, 1.0, v131
	v_rcp_f32_e32 v174, v132
	v_add_f32_e32 v132, 1.0, v134
	v_rcp_f32_e32 v128, v128
	v_rcp_f32_e32 v129, v129
	v_rcp_f32_e32 v130, v130
	v_rcp_f32_e32 v131, v131
	v_rcp_f32_e32 v175, v132
	v_ashrrev_i32_e32 v167, 31, v166
	v_lshlrev_b64 v[166:167], 10, v[166:167]
	v_pk_mul_f32 v[132:133], v[76:77], v[128:129]
	v_pk_mul_f32 v[134:135], v[78:79], v[130:131]
	v_pk_mul_f32 v[128:129], v[72:73], v[168:169]
	v_pk_mul_f32 v[130:131], v[74:75], v[174:175]
	v_lshl_add_u64 v[166:167], v[164:165], 0, v[166:167]
	s_and_b64 vcc, exec, s[4:5]
	v_cvt_pk_bf16_f32 v174, v132, v133
	v_cvt_pk_bf16_f32 v175, v134, v135
	v_cvt_pk_bf16_f32 v176, v128, v129
	v_cvt_pk_bf16_f32 v177, v130, v131
	global_store_dwordx4 v[166:167], v[174:177], off offset:-2048 sc1
	s_cbranch_vccnz .LBB0_144
	s_and_saveexec_b64 s[20:21], s[6:7]
	s_xor_b64 s[6:7], exec, s[20:21]
	s_cbranch_execnz .LBB0_263
	s_andn2_saveexec_b64 s[6:7], s[6:7]
	s_cbranch_execnz .LBB0_264

.LBB0_144:
	s_movk_i32 s1, 0x3f7f
	v_cmp_lt_i32_e64 s[6:7], s1, v162
	s_and_saveexec_b64 s[18:19], s[6:7]
	s_xor_b64 s[18:19], exec, s[18:19]
	v_add_u32_e32 v128, 0xffffc080, v162
	v_lshrrev_b32_e32 v128, 3, v128
	v_mad_u64_u32 v[166:167], s[20:21], v128, 38, v[148:149]
	s_or_saveexec_b64 s[18:19], s[18:19]
	v_add_u32_e32 v128, 0x80, v162
	v_ashrrev_i32_e32 v173, 13, v128
	v_mad_i32_i24 v163, v173, 30, 30
	s_xor_b64 exec, exec, s[18:19]
	v_add_u32_e32 v166, v163, v128
	s_or_b64 exec, exec, s[18:19]
	v_mul_f32_e32 v132, 0xbfb8aa3b, v48
	v_exp_f32_e32 v132, v132
	v_mul_f32_e32 v133, 0xbfb8aa3b, v49
	v_exp_f32_e32 v133, v133
	v_mul_f32_e32 v128, 0xbfb8aa3b, v52
	v_add_f32_e32 v132, 1.0, v132
	v_rcp_f32_e32 v168, v132
	v_add_f32_e32 v132, 1.0, v133
	v_mul_f32_e32 v133, 0xbfb8aa3b, v50
	v_mul_f32_e32 v129, 0xbfb8aa3b, v53
	v_mul_f32_e32 v130, 0xbfb8aa3b, v54
	v_mul_f32_e32 v131, 0xbfb8aa3b, v55
	v_exp_f32_e32 v133, v133
	v_mul_f32_e32 v134, 0xbfb8aa3b, v51
	v_exp_f32_e32 v128, v128
	v_exp_f32_e32 v129, v129
	v_exp_f32_e32 v130, v130
	v_exp_f32_e32 v131, v131
	v_exp_f32_e32 v134, v134
	v_rcp_f32_e32 v169, v132
	v_add_f32_e32 v132, 1.0, v133
	v_add_f32_e32 v128, 1.0, v128
	v_add_f32_e32 v129, 1.0, v129
	v_add_f32_e32 v130, 1.0, v130
	v_add_f32_e32 v131, 1.0, v131
	v_rcp_f32_e32 v174, v132
	v_add_f32_e32 v132, 1.0, v134
	v_rcp_f32_e32 v128, v128
	v_rcp_f32_e32 v129, v129
	v_rcp_f32_e32 v130, v130
	v_rcp_f32_e32 v131, v131
	v_rcp_f32_e32 v175, v132
	v_ashrrev_i32_e32 v167, 31, v166
	v_lshlrev_b64 v[166:167], 10, v[166:167]
	v_pk_mul_f32 v[132:133], v[60:61], v[128:129]
	v_pk_mul_f32 v[134:135], v[62:63], v[130:131]
	v_pk_mul_f32 v[128:129], v[56:57], v[168:169]
	v_pk_mul_f32 v[130:131], v[58:59], v[174:175]
	v_lshl_add_u64 v[166:167], v[164:165], 0, v[166:167]
	s_and_b64 vcc, exec, s[4:5]
	v_cvt_pk_bf16_f32 v174, v132, v133
	v_cvt_pk_bf16_f32 v175, v134, v135
	v_cvt_pk_bf16_f32 v176, v128, v129
	v_cvt_pk_bf16_f32 v177, v130, v131
	global_store_dwordx4 v[166:167], v[174:177], off offset:-2048 sc1
	s_cbranch_vccnz .LBB0_154
	v_mov_b64_e32 v[166:167], -1
	s_and_saveexec_b64 s[18:19], s[6:7]
	v_add_u32_e32 v144, 0xffffc080, v162
	v_lshrrev_b32_e32 v144, 3, v144
	v_mad_u64_u32 v[166:167], s[6:7], v144, 30, v[150:151]
	v_lshlrev_b64 v[166:167], 9, v[166:167]
	v_lshl_add_u64 v[166:167], v[166:167], 0, s[34:35]
	s_or_b64 exec, exec, s[18:19]
	v_cmp_lt_i64_e32 vcc, -1, v[166:167]
	s_and_saveexec_b64 s[6:7], vcc
	s_cbranch_execz .LBB0_153
	v_readlane_b32 s84, v247, 20
	v_readlane_b32 s86, v247, 22
	v_readlane_b32 s87, v247, 23
	v_add_u32_e32 v144, s0, v146
	v_readlane_b32 s85, v247, 21
	v_lshl_add_u64 v[166:167], v[166:167], 2, s[86:87]
	v_lshl_add_u64 v[166:167], v[144:145], 2, v[166:167]
	global_store_dwordx4 v[166:167], v[132:135], off offset:-4096
	global_store_dwordx4 v[166:167], v[128:131], off offset:-4080

.LBB0_154:
	s_movk_i32 s1, 0x3f6f
	v_cmp_lt_i32_e64 s[6:7], s1, v162
	s_and_saveexec_b64 s[18:19], s[6:7]
	s_xor_b64 s[18:19], exec, s[18:19]
	v_add_u32_e32 v128, 0xffffc090, v162
	v_lshrrev_b32_e32 v128, 3, v128
	v_mad_u64_u32 v[166:167], s[20:21], v128, 38, v[148:149]
	s_andn2_saveexec_b64 s[18:19], s[18:19]
	s_movk_i32 s1, 0x90
	v_add3_u32 v166, v162, v163, s1
	s_or_b64 exec, exec, s[18:19]
	v_mul_f32_e32 v132, 0xbfb8aa3b, v32
	v_exp_f32_e32 v132, v132
	v_mul_f32_e32 v133, 0xbfb8aa3b, v33
	v_exp_f32_e32 v133, v133
	v_mul_f32_e32 v128, 0xbfb8aa3b, v36
	v_add_f32_e32 v132, 1.0, v132
	v_rcp_f32_e32 v168, v132
	v_add_f32_e32 v132, 1.0, v133
	v_mul_f32_e32 v133, 0xbfb8aa3b, v34
	v_mul_f32_e32 v129, 0xbfb8aa3b, v37
	v_mul_f32_e32 v130, 0xbfb8aa3b, v38
	v_mul_f32_e32 v131, 0xbfb8aa3b, v39
	v_exp_f32_e32 v133, v133
	v_mul_f32_e32 v134, 0xbfb8aa3b, v35
	v_exp_f32_e32 v128, v128
	v_exp_f32_e32 v129, v129
	v_exp_f32_e32 v130, v130
	v_exp_f32_e32 v131, v131
	v_exp_f32_e32 v134, v134
	v_rcp_f32_e32 v169, v132
	v_add_f32_e32 v132, 1.0, v133
	v_add_f32_e32 v128, 1.0, v128
	v_add_f32_e32 v129, 1.0, v129
	v_add_f32_e32 v130, 1.0, v130
	v_add_f32_e32 v131, 1.0, v131
	v_rcp_f32_e32 v174, v132
	v_add_f32_e32 v132, 1.0, v134
	v_rcp_f32_e32 v128, v128
	v_rcp_f32_e32 v129, v129
	v_rcp_f32_e32 v130, v130
	v_rcp_f32_e32 v131, v131
	v_rcp_f32_e32 v175, v132
	v_ashrrev_i32_e32 v167, 31, v166
	v_lshlrev_b64 v[166:167], 10, v[166:167]
	v_pk_mul_f32 v[132:133], v[44:45], v[128:129]
	v_pk_mul_f32 v[134:135], v[46:47], v[130:131]
	v_pk_mul_f32 v[128:129], v[40:41], v[168:169]
	v_pk_mul_f32 v[130:131], v[42:43], v[174:175]
	v_lshl_add_u64 v[166:167], v[164:165], 0, v[166:167]
	s_and_b64 vcc, exec, s[4:5]
	v_cvt_pk_bf16_f32 v174, v132, v133
	v_cvt_pk_bf16_f32 v175, v134, v135
	v_cvt_pk_bf16_f32 v176, v128, v129
	v_cvt_pk_bf16_f32 v177, v130, v131
	global_store_dwordx4 v[166:167], v[174:177], off offset:-2048 sc1
	s_cbranch_vccnz .LBB0_164
	v_mov_b64_e32 v[166:167], -1
	s_and_saveexec_b64 s[18:19], s[6:7]
	v_add_u32_e32 v144, 0xffffc090, v162
	v_lshrrev_b32_e32 v144, 3, v144
	v_mad_u64_u32 v[166:167], s[6:7], v144, 30, v[150:151]
	v_lshlrev_b64 v[166:167], 9, v[166:167]
	v_lshl_add_u64 v[166:167], v[166:167], 0, s[34:35]
	s_or_b64 exec, exec, s[18:19]
	v_cmp_lt_i64_e32 vcc, -1, v[166:167]
	s_and_saveexec_b64 s[6:7], vcc
	s_cbranch_execz .LBB0_163
	v_readlane_b32 s84, v247, 20
	v_readlane_b32 s86, v247, 22
	v_readlane_b32 s87, v247, 23
	v_add_u32_e32 v144, s0, v146
	v_readlane_b32 s85, v247, 21
	v_lshl_add_u64 v[166:167], v[166:167], 2, s[86:87]
	v_lshl_add_u64 v[166:167], v[144:145], 2, v[166:167]
	global_store_dwordx4 v[166:167], v[132:135], off offset:-4096
	global_store_dwordx4 v[166:167], v[128:131], off offset:-4080

.LBB0_164:
	s_movk_i32 s1, 0x3f5f
	v_cmp_lt_i32_e64 s[6:7], s1, v162
	s_and_saveexec_b64 s[18:19], s[6:7]
	s_xor_b64 s[18:19], exec, s[18:19]
	v_add_u32_e32 v128, 0xffffc0a0, v162
	v_lshrrev_b32_e32 v128, 3, v128
	v_mad_u64_u32 v[168:169], s[20:21], v128, 38, v[148:149]
	s_or_saveexec_b64 s[18:19], s[18:19]
	v_add_u32_e32 v144, 0xa0, v162
	s_xor_b64 exec, exec, s[18:19]
	v_add_u32_e32 v168, v163, v144
	s_or_b64 exec, exec, s[18:19]
	v_mul_f32_e32 v132, 0xbfb8aa3b, v16
	v_exp_f32_e32 v132, v132
	v_mul_f32_e32 v133, 0xbfb8aa3b, v17
	v_exp_f32_e32 v133, v133
	v_mul_f32_e32 v128, 0xbfb8aa3b, v20
	v_add_f32_e32 v132, 1.0, v132
	v_rcp_f32_e32 v174, v132
	v_add_f32_e32 v132, 1.0, v133
	v_mul_f32_e32 v133, 0xbfb8aa3b, v18
	v_mul_f32_e32 v129, 0xbfb8aa3b, v21
	v_mul_f32_e32 v130, 0xbfb8aa3b, v22
	v_mul_f32_e32 v131, 0xbfb8aa3b, v23
	v_exp_f32_e32 v133, v133
	v_mul_f32_e32 v134, 0xbfb8aa3b, v19
	v_exp_f32_e32 v128, v128
	v_exp_f32_e32 v129, v129
	v_exp_f32_e32 v130, v130
	v_exp_f32_e32 v131, v131
	v_exp_f32_e32 v134, v134
	v_rcp_f32_e32 v175, v132
	v_add_f32_e32 v132, 1.0, v133
	v_add_f32_e32 v128, 1.0, v128
	v_add_f32_e32 v129, 1.0, v129
	v_add_f32_e32 v130, 1.0, v130
	v_add_f32_e32 v131, 1.0, v131
	v_rcp_f32_e32 v176, v132
	v_add_f32_e32 v132, 1.0, v134
	v_rcp_f32_e32 v128, v128
	v_rcp_f32_e32 v129, v129
	v_rcp_f32_e32 v130, v130
	v_rcp_f32_e32 v131, v131
	v_rcp_f32_e32 v177, v132
	v_ashrrev_i32_e32 v169, 31, v168
	v_mul_i32_i24_e32 v166, 30, v173
	v_lshlrev_b64 v[168:169], 10, v[168:169]
	v_ashrrev_i32_e32 v167, 31, v166
	v_pk_mul_f32 v[132:133], v[28:29], v[128:129]
	v_pk_mul_f32 v[134:135], v[30:31], v[130:131]
	v_pk_mul_f32 v[128:129], v[24:25], v[174:175]
	v_pk_mul_f32 v[130:131], v[26:27], v[176:177]
	v_lshl_add_u64 v[168:169], v[164:165], 0, v[168:169]
	s_and_b64 vcc, exec, s[4:5]
	v_cvt_pk_bf16_f32 v174, v132, v133
	v_cvt_pk_bf16_f32 v175, v134, v135
	v_cvt_pk_bf16_f32 v176, v128, v129
	v_cvt_pk_bf16_f32 v177, v130, v131
	global_store_dwordx4 v[168:169], v[174:177], off offset:-2048 sc1
	s_cbranch_vccnz .LBB0_174
	s_and_saveexec_b64 s[18:19], s[6:7]
	s_xor_b64 s[6:7], exec, s[18:19]
	s_cbranch_execnz .LBB0_265
	s_andn2_saveexec_b64 s[6:7], s[6:7]
	s_cbranch_execnz .LBB0_266

.LBB0_174:
	s_movk_i32 s1, 0x3f4f
	v_cmp_lt_i32_e64 s[6:7], s1, v162
	s_and_saveexec_b64 s[18:19], s[6:7]
	s_xor_b64 s[18:19], exec, s[18:19]
	v_add_u32_e32 v128, 0xffffc0b0, v162
	v_lshrrev_b32_e32 v128, 3, v128
	v_mad_u64_u32 v[168:169], s[20:21], v128, 38, v[148:149]
	s_or_saveexec_b64 s[18:19], s[18:19]
	v_add_u32_e32 v144, 0xb0, v162
	s_xor_b64 exec, exec, s[18:19]
	v_add_u32_e32 v168, v163, v144
	s_or_b64 exec, exec, s[18:19]
	v_mul_f32_e32 v132, 0xbfb8aa3b, v0
	v_exp_f32_e32 v132, v132
	v_mul_f32_e32 v133, 0xbfb8aa3b, v1
	v_exp_f32_e32 v133, v133
	v_mul_f32_e32 v128, 0xbfb8aa3b, v4
	v_add_f32_e32 v132, 1.0, v132
	v_rcp_f32_e32 v174, v132
	v_add_f32_e32 v132, 1.0, v133
	v_mul_f32_e32 v133, 0xbfb8aa3b, v2
	v_mul_f32_e32 v129, 0xbfb8aa3b, v5
	v_mul_f32_e32 v130, 0xbfb8aa3b, v6
	v_mul_f32_e32 v131, 0xbfb8aa3b, v7
	v_exp_f32_e32 v133, v133
	v_mul_f32_e32 v134, 0xbfb8aa3b, v3
	v_exp_f32_e32 v128, v128
	v_exp_f32_e32 v129, v129
	v_exp_f32_e32 v130, v130
	v_exp_f32_e32 v131, v131
	v_exp_f32_e32 v134, v134
	v_rcp_f32_e32 v175, v132
	v_add_f32_e32 v132, 1.0, v133
	v_add_f32_e32 v128, 1.0, v128
	v_add_f32_e32 v129, 1.0, v129
	v_add_f32_e32 v130, 1.0, v130
	v_add_f32_e32 v131, 1.0, v131
	v_rcp_f32_e32 v176, v132
	v_add_f32_e32 v132, 1.0, v134
	v_rcp_f32_e32 v128, v128
	v_rcp_f32_e32 v129, v129
	v_rcp_f32_e32 v130, v130
	v_rcp_f32_e32 v131, v131
	v_rcp_f32_e32 v177, v132
	v_ashrrev_i32_e32 v169, 31, v168
	v_lshlrev_b64 v[168:169], 10, v[168:169]
	v_pk_mul_f32 v[132:133], v[12:13], v[128:129]
	v_pk_mul_f32 v[134:135], v[14:15], v[130:131]
	v_pk_mul_f32 v[128:129], v[8:9], v[174:175]
	v_pk_mul_f32 v[130:131], v[10:11], v[176:177]
	v_lshl_add_u64 v[164:165], v[164:165], 0, v[168:169]
	s_and_b64 vcc, exec, s[4:5]
	v_cvt_pk_bf16_f32 v174, v132, v133
	v_cvt_pk_bf16_f32 v175, v134, v135
	v_cvt_pk_bf16_f32 v176, v128, v129
	v_cvt_pk_bf16_f32 v177, v130, v131
	global_store_dwordx4 v[164:165], v[174:177], off offset:-2048 sc1
	s_cbranch_vccnz .LBB0_184
	s_and_saveexec_b64 s[4:5], s[6:7]
	s_xor_b64 s[4:5], exec, s[4:5]
	s_cbranch_execnz .LBB0_267
	s_andn2_saveexec_b64 s[4:5], s[4:5]
	s_cbranch_execnz .LBB0_268

.LBB0_185:
	s_and_b64 vcc, exec, s[4:5]
	s_cbranch_vccz .LBB0_187
	s_lshl_b32 s0, s2, 8
	s_and_b32 s0, s0, 0x100
	v_or_b32_e32 v130, s0, v146
	s_and_b32 s0, s2, 6
	s_cmp_eq_u32 s0, 2
	v_readlane_b32 s0, v247, 27
	v_readlane_b32 s1, v247, 29
	s_mov_b32 s3, 0x1907800
	s_mov_b32 s4, 0x1100000
	s_cselect_b32 s0, s82, s0
	s_cselect_b32 s1, s83, s1
	s_cselect_b32 s3, s3, 0x1987800
	s_cselect_b32 s4, s4, 0x1900000
	s_cmp_gt_i32 s16, 63
	v_lshlrev_b32_e32 v144, 1, v130
	v_lshl_add_u64 v[128:129], s[0:1], 0, v[144:145]
	s_cselect_b32 s0, s3, s4
	v_readlane_b32 s4, v247, 20
	s_lshl_b32 s0, s0, 2
	v_readlane_b32 s6, v247, 22
	v_readlane_b32 s7, v247, 23
	s_add_u32 s0, s6, s0
	s_addc_u32 s1, s7, 0
	v_lshlrev_b32_e32 v144, 2, v130
	v_ashrrev_i32_e32 v163, 31, v162
	v_lshl_add_u64 v[130:131], s[0:1], 0, v[144:145]
	v_lshlrev_b64 v[132:133], 11, v[162:163]
	v_lshl_add_u64 v[164:165], v[130:131], 0, v[132:133]
	v_lshlrev_b64 v[132:133], 10, v[162:163]
	v_lshl_add_u64 v[166:167], v[128:129], 0, v[132:133]
	global_store_dwordx4 v[164:165], v[124:127], off
	global_store_dwordx4 v[164:165], v[120:123], off offset:16
	v_cvt_pk_bf16_f32 v132, v124, v125
	v_cvt_pk_bf16_f32 v133, v126, v127
	v_cvt_pk_bf16_f32 v134, v120, v121
	v_cvt_pk_bf16_f32 v135, v122, v123
	global_store_dwordx4 v[166:167], v[132:135], off sc1
	global_store_dwordx4 v[164:165], v[116:119], off offset:512
	global_store_dwordx4 v[164:165], v[112:115], off offset:528
	v_cvt_pk_bf16_f32 v132, v116, v117
	v_cvt_pk_bf16_f32 v133, v118, v119
	v_cvt_pk_bf16_f32 v134, v112, v113
	v_cvt_pk_bf16_f32 v135, v114, v115
	global_store_dwordx4 v[166:167], v[132:135], off offset:256 sc1
	v_readlane_b32 s5, v247, 21
	s_nop 0
	v_or_b32_e32 v132, 16, v162
	v_ashrrev_i32_e32 v133, 31, v132
	v_lshlrev_b64 v[134:135], 11, v[132:133]
	v_lshl_add_u64 v[164:165], v[130:131], 0, v[134:135]
	v_lshlrev_b64 v[132:133], 10, v[132:133]
	v_lshl_add_u64 v[166:167], v[128:129], 0, v[132:133]
	global_store_dwordx4 v[164:165], v[108:111], off
	global_store_dwordx4 v[164:165], v[104:107], off offset:16
	v_cvt_pk_bf16_f32 v132, v108, v109
	v_cvt_pk_bf16_f32 v133, v110, v111
	v_cvt_pk_bf16_f32 v134, v104, v105
	v_cvt_pk_bf16_f32 v135, v106, v107
	global_store_dwordx4 v[166:167], v[132:135], off sc1
	global_store_dwordx4 v[164:165], v[100:103], off offset:512
	global_store_dwordx4 v[164:165], v[96:99], off offset:528
	v_cvt_pk_bf16_f32 v132, v100, v101
	v_cvt_pk_bf16_f32 v133, v102, v103
	v_cvt_pk_bf16_f32 v134, v96, v97
	v_cvt_pk_bf16_f32 v135, v98, v99
	global_store_dwordx4 v[166:167], v[132:135], off offset:256 sc1
	s_nop 1
	v_or_b32_e32 v132, 32, v162
	v_ashrrev_i32_e32 v133, 31, v132
	v_lshlrev_b64 v[134:135], 11, v[132:133]
	v_lshl_add_u64 v[164:165], v[130:131], 0, v[134:135]
	v_lshlrev_b64 v[132:133], 10, v[132:133]
	v_lshl_add_u64 v[166:167], v[128:129], 0, v[132:133]
	global_store_dwordx4 v[164:165], v[92:95], off
	global_store_dwordx4 v[164:165], v[88:91], off offset:16
	v_cvt_pk_bf16_f32 v132, v92, v93
	v_cvt_pk_bf16_f32 v133, v94, v95
	v_cvt_pk_bf16_f32 v134, v88, v89
	v_cvt_pk_bf16_f32 v135, v90, v91
	global_store_dwordx4 v[166:167], v[132:135], off sc1
	global_store_dwordx4 v[164:165], v[84:87], off offset:512
	global_store_dwordx4 v[164:165], v[80:83], off offset:528
	v_cvt_pk_bf16_f32 v132, v84, v85
	v_cvt_pk_bf16_f32 v133, v86, v87
	v_cvt_pk_bf16_f32 v134, v80, v81
	v_cvt_pk_bf16_f32 v135, v82, v83
	global_store_dwordx4 v[166:167], v[132:135], off offset:256 sc1
	s_nop 1
	v_or_b32_e32 v132, 48, v162
	v_ashrrev_i32_e32 v133, 31, v132
	v_lshlrev_b64 v[134:135], 11, v[132:133]
	v_lshl_add_u64 v[164:165], v[130:131], 0, v[134:135]
	v_lshlrev_b64 v[132:133], 10, v[132:133]
	v_lshl_add_u64 v[166:167], v[128:129], 0, v[132:133]
	global_store_dwordx4 v[164:165], v[76:79], off
	global_store_dwordx4 v[164:165], v[72:75], off offset:16
	v_cvt_pk_bf16_f32 v132, v76, v77
	v_cvt_pk_bf16_f32 v133, v78, v79
	v_cvt_pk_bf16_f32 v134, v72, v73
	v_cvt_pk_bf16_f32 v135, v74, v75
	global_store_dwordx4 v[166:167], v[132:135], off sc1
	global_store_dwordx4 v[164:165], v[68:71], off offset:512
	global_store_dwordx4 v[164:165], v[64:67], off offset:528
	v_cvt_pk_bf16_f32 v132, v68, v69
	v_cvt_pk_bf16_f32 v133, v70, v71
	v_cvt_pk_bf16_f32 v134, v64, v65
	v_cvt_pk_bf16_f32 v135, v66, v67
	global_store_dwordx4 v[166:167], v[132:135], off offset:256 sc1
	s_nop 1
	v_add_u32_e32 v132, 0x80, v162
	v_ashrrev_i32_e32 v133, 31, v132
	v_lshlrev_b64 v[134:135], 11, v[132:133]
	v_lshl_add_u64 v[164:165], v[130:131], 0, v[134:135]
	v_lshlrev_b64 v[132:133], 10, v[132:133]
	v_lshl_add_u64 v[166:167], v[128:129], 0, v[132:133]
	global_store_dwordx4 v[164:165], v[60:63], off
	global_store_dwordx4 v[164:165], v[56:59], off offset:16
	v_cvt_pk_bf16_f32 v132, v60, v61
	v_cvt_pk_bf16_f32 v133, v62, v63
	v_cvt_pk_bf16_f32 v134, v56, v57
	v_cvt_pk_bf16_f32 v135, v58, v59
	global_store_dwordx4 v[166:167], v[132:135], off sc1
	global_store_dwordx4 v[164:165], v[52:55], off offset:512
	global_store_dwordx4 v[164:165], v[48:51], off offset:528
	v_cvt_pk_bf16_f32 v132, v52, v53
	v_cvt_pk_bf16_f32 v133, v54, v55
	v_cvt_pk_bf16_f32 v134, v48, v49
	v_cvt_pk_bf16_f32 v135, v50, v51
	global_store_dwordx4 v[166:167], v[132:135], off offset:256 sc1
	s_nop 1
	v_add_u32_e32 v132, 0x90, v162
	v_ashrrev_i32_e32 v133, 31, v132
	v_lshlrev_b64 v[134:135], 11, v[132:133]
	v_lshl_add_u64 v[164:165], v[130:131], 0, v[134:135]
	v_lshlrev_b64 v[132:133], 10, v[132:133]
	v_lshl_add_u64 v[166:167], v[128:129], 0, v[132:133]
	global_store_dwordx4 v[164:165], v[44:47], off
	global_store_dwordx4 v[164:165], v[40:43], off offset:16
	v_cvt_pk_bf16_f32 v132, v44, v45
	v_cvt_pk_bf16_f32 v133, v46, v47
	v_cvt_pk_bf16_f32 v134, v40, v41
	v_cvt_pk_bf16_f32 v135, v42, v43
	global_store_dwordx4 v[166:167], v[132:135], off sc1
	global_store_dwordx4 v[164:165], v[36:39], off offset:512
	global_store_dwordx4 v[164:165], v[32:35], off offset:528
	v_cvt_pk_bf16_f32 v132, v36, v37
	v_cvt_pk_bf16_f32 v133, v38, v39
	v_cvt_pk_bf16_f32 v134, v32, v33
	v_cvt_pk_bf16_f32 v135, v34, v35
	global_store_dwordx4 v[166:167], v[132:135], off offset:256 sc1
	s_nop 1
	v_add_u32_e32 v132, 0xa0, v162
	v_ashrrev_i32_e32 v133, 31, v132
	v_lshlrev_b64 v[134:135], 11, v[132:133]
	v_lshl_add_u64 v[164:165], v[130:131], 0, v[134:135]
	v_lshlrev_b64 v[132:133], 10, v[132:133]
	v_lshl_add_u64 v[166:167], v[128:129], 0, v[132:133]
	global_store_dwordx4 v[164:165], v[28:31], off
	global_store_dwordx4 v[164:165], v[24:27], off offset:16
	v_cvt_pk_bf16_f32 v132, v28, v29
	v_cvt_pk_bf16_f32 v133, v30, v31
	v_cvt_pk_bf16_f32 v134, v24, v25
	v_cvt_pk_bf16_f32 v135, v26, v27
	global_store_dwordx4 v[166:167], v[132:135], off sc1
	global_store_dwordx4 v[164:165], v[20:23], off offset:512
	global_store_dwordx4 v[164:165], v[16:19], off offset:528
	v_cvt_pk_bf16_f32 v132, v20, v21
	v_cvt_pk_bf16_f32 v133, v22, v23
	v_cvt_pk_bf16_f32 v134, v16, v17
	v_cvt_pk_bf16_f32 v135, v18, v19
	global_store_dwordx4 v[166:167], v[132:135], off offset:256 sc1
	s_nop 1
	v_add_u32_e32 v132, 0xb0, v162
	v_ashrrev_i32_e32 v133, 31, v132
	v_lshlrev_b64 v[134:135], 11, v[132:133]
	v_lshl_add_u64 v[134:135], v[130:131], 0, v[134:135]
	v_lshlrev_b64 v[130:131], 10, v[132:133]
	v_lshl_add_u64 v[132:133], v[128:129], 0, v[130:131]
	global_store_dwordx4 v[134:135], v[12:15], off
	global_store_dwordx4 v[134:135], v[8:11], off offset:16
	v_cvt_pk_bf16_f32 v128, v12, v13
	v_cvt_pk_bf16_f32 v129, v14, v15
	v_cvt_pk_bf16_f32 v130, v8, v9
	v_cvt_pk_bf16_f32 v131, v10, v11
	global_store_dwordx4 v[132:133], v[128:131], off sc1
	global_store_dwordx4 v[134:135], v[4:7], off offset:512
	global_store_dwordx4 v[134:135], v[0:3], off offset:528
	v_cvt_pk_bf16_f32 v128, v4, v5
	v_cvt_pk_bf16_f32 v129, v6, v7
	v_cvt_pk_bf16_f32 v130, v0, v1
	v_cvt_pk_bf16_f32 v131, v2, v3
	global_store_dwordx4 v[132:133], v[128:131], off offset:256 sc1

.LBB0_201:
	v_lshlrev_b32_e32 v144, 1, v146
	v_ashrrev_i32_e32 v163, 31, v162
	v_lshl_add_u64 v[164:165], s[16:17], 0, v[144:145]
	v_lshlrev_b64 v[120:121], 10, v[162:163]
	v_lshl_add_u64 v[166:167], v[164:165], 0, v[120:121]
	v_cvt_pk_bf16_f32 v120, v128, v129
	v_cvt_pk_bf16_f32 v121, v130, v131
	v_cvt_pk_bf16_f32 v122, v132, v133
	v_cvt_pk_bf16_f32 v123, v134, v135
	s_and_b64 vcc, exec, s[4:5]
	s_mov_b64 s[2:3], -1
	global_store_dwordx4 v[166:167], v[120:123], off sc1
	s_cbranch_vccnz .LBB0_203
	s_nop 0
	v_mul_f32_e32 v121, 0xbfb8aa3b, v112
	v_exp_f32_e32 v121, v121
	v_mul_f32_e32 v122, 0xbfb8aa3b, v117
	v_mul_f32_e32 v123, 0xbfb8aa3b, v113
	v_exp_f32_e32 v122, v122
	v_exp_f32_e32 v123, v123
	v_add_f32_e32 v121, 1.0, v121
	v_rcp_f32_e32 v124, v121
	v_add_f32_e32 v121, 1.0, v122
	v_add_f32_e32 v122, 1.0, v123
	v_mul_f32_e32 v123, 0xbfb8aa3b, v114
	v_mul_f32_e32 v126, 0xbfb8aa3b, v119
	v_exp_f32_e32 v123, v123
	v_exp_f32_e32 v126, v126
	v_mul_f32_e32 v120, 0xbfb8aa3b, v116
	v_rcp_f32_e32 v125, v122
	v_mul_f32_e32 v122, 0xbfb8aa3b, v118
	v_add_f32_e32 v127, 1.0, v123
	v_add_f32_e32 v123, 1.0, v126
	v_mul_f32_e32 v126, 0xbfb8aa3b, v115
	v_exp_f32_e32 v120, v120
	v_exp_f32_e32 v122, v122
	v_exp_f32_e32 v128, v126
	v_rcp_f32_e32 v126, v127
	v_add_f32_e32 v120, 1.0, v120
	v_add_f32_e32 v122, 1.0, v122
	v_add_f32_e32 v127, 1.0, v128
	v_rcp_f32_e32 v120, v120
	v_rcp_f32_e32 v121, v121
	v_rcp_f32_e32 v122, v122
	v_rcp_f32_e32 v123, v123
	v_rcp_f32_e32 v127, v127
	v_pk_mul_f32 v[120:121], v[116:117], v[120:121]
	v_pk_mul_f32 v[124:125], v[112:113], v[124:125]
	v_pk_mul_f32 v[122:123], v[118:119], v[122:123]
	v_pk_mul_f32 v[126:127], v[114:115], v[126:127]
	v_pk_mul_f32 v[122:123], v[122:123], s[6:7] op_sel_hi:[1,0]
	v_pk_mul_f32 v[120:121], v[120:121], s[6:7] op_sel_hi:[1,0]
	v_pk_mul_f32 v[126:127], v[126:127], s[6:7] op_sel_hi:[1,0]
	v_pk_mul_f32 v[124:125], v[124:125], s[6:7] op_sel_hi:[1,0]
	s_mov_b64 s[2:3], 0

.LBB0_205:
	v_cvt_pk_bf16_f32 v112, v120, v121
	v_cvt_pk_bf16_f32 v113, v122, v123
	s_nop 0
	v_cvt_pk_bf16_f32 v114, v124, v125
	v_cvt_pk_bf16_f32 v115, v126, v127
	s_and_b64 vcc, exec, s[4:5]
	s_mov_b64 s[2:3], -1
	global_store_dwordx4 v[166:167], v[112:115], off offset:256 sc1
	s_cbranch_vccnz .LBB0_207
	s_nop 0
	v_mul_f32_e32 v113, 0xbfb8aa3b, v104
	v_exp_f32_e32 v113, v113
	v_mul_f32_e32 v114, 0xbfb8aa3b, v109
	v_mul_f32_e32 v115, 0xbfb8aa3b, v105
	v_exp_f32_e32 v114, v114
	v_exp_f32_e32 v115, v115
	v_add_f32_e32 v113, 1.0, v113
	v_rcp_f32_e32 v116, v113
	v_add_f32_e32 v113, 1.0, v114
	v_add_f32_e32 v114, 1.0, v115
	v_mul_f32_e32 v115, 0xbfb8aa3b, v106
	v_mul_f32_e32 v118, 0xbfb8aa3b, v111
	v_exp_f32_e32 v115, v115
	v_exp_f32_e32 v118, v118
	v_mul_f32_e32 v112, 0xbfb8aa3b, v108
	v_rcp_f32_e32 v117, v114
	v_mul_f32_e32 v114, 0xbfb8aa3b, v110
	v_add_f32_e32 v119, 1.0, v115
	v_add_f32_e32 v115, 1.0, v118
	v_mul_f32_e32 v118, 0xbfb8aa3b, v107
	v_exp_f32_e32 v112, v112
	v_exp_f32_e32 v114, v114
	v_exp_f32_e32 v120, v118
	v_rcp_f32_e32 v118, v119
	v_add_f32_e32 v112, 1.0, v112
	v_add_f32_e32 v114, 1.0, v114
	v_add_f32_e32 v119, 1.0, v120
	v_rcp_f32_e32 v112, v112
	v_rcp_f32_e32 v113, v113
	v_rcp_f32_e32 v114, v114
	v_rcp_f32_e32 v115, v115
	v_rcp_f32_e32 v119, v119
	v_pk_mul_f32 v[112:113], v[108:109], v[112:113]
	v_pk_mul_f32 v[116:117], v[104:105], v[116:117]
	v_pk_mul_f32 v[114:115], v[110:111], v[114:115]
	v_pk_mul_f32 v[118:119], v[106:107], v[118:119]
	v_pk_mul_f32 v[114:115], v[114:115], s[6:7] op_sel_hi:[1,0]
	v_pk_mul_f32 v[112:113], v[112:113], s[6:7] op_sel_hi:[1,0]
	v_pk_mul_f32 v[118:119], v[118:119], s[6:7] op_sel_hi:[1,0]
	v_pk_mul_f32 v[116:117], v[116:117], s[6:7] op_sel_hi:[1,0]
	s_mov_b64 s[2:3], 0

.LBB0_209:
	v_or_b32_e32 v104, 16, v162
	v_ashrrev_i32_e32 v105, 31, v104
	v_lshlrev_b64 v[104:105], 10, v[104:105]
	v_lshl_add_u64 v[120:121], v[164:165], 0, v[104:105]
	v_cvt_pk_bf16_f32 v104, v112, v113
	v_cvt_pk_bf16_f32 v105, v114, v115
	v_cvt_pk_bf16_f32 v106, v116, v117
	v_cvt_pk_bf16_f32 v107, v118, v119
	s_and_b64 vcc, exec, s[4:5]
	s_mov_b64 s[2:3], -1
	global_store_dwordx4 v[120:121], v[104:107], off sc1
	s_cbranch_vccnz .LBB0_211
	s_nop 0
	v_mul_f32_e32 v105, 0xbfb8aa3b, v96
	v_exp_f32_e32 v105, v105
	v_mul_f32_e32 v106, 0xbfb8aa3b, v101
	v_mul_f32_e32 v107, 0xbfb8aa3b, v97
	v_exp_f32_e32 v106, v106
	v_exp_f32_e32 v107, v107
	v_add_f32_e32 v105, 1.0, v105
	v_rcp_f32_e32 v108, v105
	v_add_f32_e32 v105, 1.0, v106
	v_add_f32_e32 v106, 1.0, v107
	v_mul_f32_e32 v107, 0xbfb8aa3b, v98
	v_mul_f32_e32 v110, 0xbfb8aa3b, v103
	v_exp_f32_e32 v107, v107
	v_exp_f32_e32 v110, v110
	v_mul_f32_e32 v104, 0xbfb8aa3b, v100
	v_rcp_f32_e32 v109, v106
	v_mul_f32_e32 v106, 0xbfb8aa3b, v102
	v_add_f32_e32 v111, 1.0, v107
	v_add_f32_e32 v107, 1.0, v110
	v_mul_f32_e32 v110, 0xbfb8aa3b, v99
	v_exp_f32_e32 v104, v104
	v_exp_f32_e32 v106, v106
	v_exp_f32_e32 v112, v110
	v_rcp_f32_e32 v110, v111
	v_add_f32_e32 v104, 1.0, v104
	v_add_f32_e32 v106, 1.0, v106
	v_add_f32_e32 v111, 1.0, v112
	v_rcp_f32_e32 v104, v104
	v_rcp_f32_e32 v105, v105
	v_rcp_f32_e32 v106, v106
	v_rcp_f32_e32 v107, v107
	v_rcp_f32_e32 v111, v111
	v_pk_mul_f32 v[104:105], v[100:101], v[104:105]
	v_pk_mul_f32 v[108:109], v[96:97], v[108:109]
	v_pk_mul_f32 v[106:107], v[102:103], v[106:107]
	v_pk_mul_f32 v[110:111], v[98:99], v[110:111]
	v_pk_mul_f32 v[106:107], v[106:107], s[6:7] op_sel_hi:[1,0]
	v_pk_mul_f32 v[104:105], v[104:105], s[6:7] op_sel_hi:[1,0]
	v_pk_mul_f32 v[110:111], v[110:111], s[6:7] op_sel_hi:[1,0]
	v_pk_mul_f32 v[108:109], v[108:109], s[6:7] op_sel_hi:[1,0]
	s_mov_b64 s[2:3], 0

.LBB0_213:
	v_cvt_pk_bf16_f32 v96, v104, v105
	v_cvt_pk_bf16_f32 v97, v106, v107
	s_nop 0
	v_cvt_pk_bf16_f32 v98, v108, v109
	v_cvt_pk_bf16_f32 v99, v110, v111
	s_and_b64 vcc, exec, s[4:5]
	s_mov_b64 s[2:3], -1
	global_store_dwordx4 v[120:121], v[96:99], off offset:256 sc1
	s_cbranch_vccnz .LBB0_215
	s_nop 0
	v_mul_f32_e32 v97, 0xbfb8aa3b, v88
	v_exp_f32_e32 v97, v97
	v_mul_f32_e32 v98, 0xbfb8aa3b, v93
	v_mul_f32_e32 v99, 0xbfb8aa3b, v89
	v_exp_f32_e32 v98, v98
	v_exp_f32_e32 v99, v99
	v_add_f32_e32 v97, 1.0, v97
	v_rcp_f32_e32 v100, v97
	v_add_f32_e32 v97, 1.0, v98
	v_add_f32_e32 v98, 1.0, v99
	v_mul_f32_e32 v99, 0xbfb8aa3b, v90
	v_mul_f32_e32 v102, 0xbfb8aa3b, v95
	v_exp_f32_e32 v99, v99
	v_exp_f32_e32 v102, v102
	v_mul_f32_e32 v96, 0xbfb8aa3b, v92
	v_rcp_f32_e32 v101, v98
	v_mul_f32_e32 v98, 0xbfb8aa3b, v94
	v_add_f32_e32 v103, 1.0, v99
	v_add_f32_e32 v99, 1.0, v102
	v_mul_f32_e32 v102, 0xbfb8aa3b, v91
	v_exp_f32_e32 v96, v96
	v_exp_f32_e32 v98, v98
	v_exp_f32_e32 v104, v102
	v_rcp_f32_e32 v102, v103
	v_add_f32_e32 v96, 1.0, v96
	v_add_f32_e32 v98, 1.0, v98
	v_add_f32_e32 v103, 1.0, v104
	v_rcp_f32_e32 v96, v96
	v_rcp_f32_e32 v97, v97
	v_rcp_f32_e32 v98, v98
	v_rcp_f32_e32 v99, v99
	v_rcp_f32_e32 v103, v103
	v_pk_mul_f32 v[96:97], v[92:93], v[96:97]
	v_pk_mul_f32 v[100:101], v[88:89], v[100:101]
	v_pk_mul_f32 v[98:99], v[94:95], v[98:99]
	v_pk_mul_f32 v[102:103], v[90:91], v[102:103]
	v_pk_mul_f32 v[98:99], v[98:99], s[6:7] op_sel_hi:[1,0]
	v_pk_mul_f32 v[96:97], v[96:97], s[6:7] op_sel_hi:[1,0]
	v_pk_mul_f32 v[102:103], v[102:103], s[6:7] op_sel_hi:[1,0]
	v_pk_mul_f32 v[100:101], v[100:101], s[6:7] op_sel_hi:[1,0]
	s_mov_b64 s[2:3], 0

.LBB0_217:
	v_or_b32_e32 v88, 32, v162
	v_ashrrev_i32_e32 v89, 31, v88
	v_lshlrev_b64 v[88:89], 10, v[88:89]
	v_lshl_add_u64 v[104:105], v[164:165], 0, v[88:89]
	v_cvt_pk_bf16_f32 v88, v96, v97
	v_cvt_pk_bf16_f32 v89, v98, v99
	v_cvt_pk_bf16_f32 v90, v100, v101
	v_cvt_pk_bf16_f32 v91, v102, v103
	s_and_b64 vcc, exec, s[4:5]
	s_mov_b64 s[2:3], -1
	global_store_dwordx4 v[104:105], v[88:91], off sc1
	s_cbranch_vccnz .LBB0_219
	s_nop 0
	v_mul_f32_e32 v89, 0xbfb8aa3b, v80
	v_exp_f32_e32 v89, v89
	v_mul_f32_e32 v90, 0xbfb8aa3b, v85
	v_mul_f32_e32 v91, 0xbfb8aa3b, v81
	v_exp_f32_e32 v90, v90
	v_exp_f32_e32 v91, v91
	v_add_f32_e32 v89, 1.0, v89
	v_rcp_f32_e32 v92, v89
	v_add_f32_e32 v89, 1.0, v90
	v_add_f32_e32 v90, 1.0, v91
	v_mul_f32_e32 v91, 0xbfb8aa3b, v82
	v_mul_f32_e32 v94, 0xbfb8aa3b, v87
	v_exp_f32_e32 v91, v91
	v_exp_f32_e32 v94, v94
	v_mul_f32_e32 v88, 0xbfb8aa3b, v84
	v_rcp_f32_e32 v93, v90
	v_mul_f32_e32 v90, 0xbfb8aa3b, v86
	v_add_f32_e32 v95, 1.0, v91
	v_add_f32_e32 v91, 1.0, v94
	v_mul_f32_e32 v94, 0xbfb8aa3b, v83
	v_exp_f32_e32 v88, v88
	v_exp_f32_e32 v90, v90
	v_exp_f32_e32 v96, v94
	v_rcp_f32_e32 v94, v95
	v_add_f32_e32 v88, 1.0, v88
	v_add_f32_e32 v90, 1.0, v90
	v_add_f32_e32 v95, 1.0, v96
	v_rcp_f32_e32 v88, v88
	v_rcp_f32_e32 v89, v89
	v_rcp_f32_e32 v90, v90
	v_rcp_f32_e32 v91, v91
	v_rcp_f32_e32 v95, v95
	v_pk_mul_f32 v[88:89], v[84:85], v[88:89]
	v_pk_mul_f32 v[92:93], v[80:81], v[92:93]
	v_pk_mul_f32 v[90:91], v[86:87], v[90:91]
	v_pk_mul_f32 v[94:95], v[82:83], v[94:95]
	v_pk_mul_f32 v[90:91], v[90:91], s[6:7] op_sel_hi:[1,0]
	v_pk_mul_f32 v[88:89], v[88:89], s[6:7] op_sel_hi:[1,0]
	v_pk_mul_f32 v[94:95], v[94:95], s[6:7] op_sel_hi:[1,0]
	v_pk_mul_f32 v[92:93], v[92:93], s[6:7] op_sel_hi:[1,0]
	s_mov_b64 s[2:3], 0

.LBB0_221:
	v_cvt_pk_bf16_f32 v80, v88, v89
	v_cvt_pk_bf16_f32 v81, v90, v91
	s_nop 0
	v_cvt_pk_bf16_f32 v82, v92, v93
	v_cvt_pk_bf16_f32 v83, v94, v95
	s_and_b64 vcc, exec, s[4:5]
	s_mov_b64 s[2:3], -1
	global_store_dwordx4 v[104:105], v[80:83], off offset:256 sc1
	s_cbranch_vccnz .LBB0_223
	s_nop 0
	v_mul_f32_e32 v81, 0xbfb8aa3b, v72
	v_exp_f32_e32 v81, v81
	v_mul_f32_e32 v82, 0xbfb8aa3b, v77
	v_mul_f32_e32 v83, 0xbfb8aa3b, v73
	v_exp_f32_e32 v82, v82
	v_exp_f32_e32 v83, v83
	v_add_f32_e32 v81, 1.0, v81
	v_rcp_f32_e32 v84, v81
	v_add_f32_e32 v81, 1.0, v82
	v_add_f32_e32 v82, 1.0, v83
	v_mul_f32_e32 v83, 0xbfb8aa3b, v74
	v_mul_f32_e32 v86, 0xbfb8aa3b, v79
	v_exp_f32_e32 v83, v83
	v_exp_f32_e32 v86, v86
	v_mul_f32_e32 v80, 0xbfb8aa3b, v76
	v_rcp_f32_e32 v85, v82
	v_mul_f32_e32 v82, 0xbfb8aa3b, v78
	v_add_f32_e32 v87, 1.0, v83
	v_add_f32_e32 v83, 1.0, v86
	v_mul_f32_e32 v86, 0xbfb8aa3b, v75
	v_exp_f32_e32 v80, v80
	v_exp_f32_e32 v82, v82
	v_exp_f32_e32 v88, v86
	v_rcp_f32_e32 v86, v87
	v_add_f32_e32 v80, 1.0, v80
	v_add_f32_e32 v82, 1.0, v82
	v_add_f32_e32 v87, 1.0, v88
	v_rcp_f32_e32 v80, v80
	v_rcp_f32_e32 v81, v81
	v_rcp_f32_e32 v82, v82
	v_rcp_f32_e32 v83, v83
	v_rcp_f32_e32 v87, v87
	v_pk_mul_f32 v[80:81], v[76:77], v[80:81]
	v_pk_mul_f32 v[84:85], v[72:73], v[84:85]
	v_pk_mul_f32 v[82:83], v[78:79], v[82:83]
	v_pk_mul_f32 v[86:87], v[74:75], v[86:87]
	v_pk_mul_f32 v[82:83], v[82:83], s[6:7] op_sel_hi:[1,0]
	v_pk_mul_f32 v[80:81], v[80:81], s[6:7] op_sel_hi:[1,0]
	v_pk_mul_f32 v[86:87], v[86:87], s[6:7] op_sel_hi:[1,0]
	v_pk_mul_f32 v[84:85], v[84:85], s[6:7] op_sel_hi:[1,0]
	s_mov_b64 s[2:3], 0

.LBB0_225:
	v_or_b32_e32 v72, 48, v162
	v_ashrrev_i32_e32 v73, 31, v72
	v_lshlrev_b64 v[72:73], 10, v[72:73]
	v_lshl_add_u64 v[88:89], v[164:165], 0, v[72:73]
	v_cvt_pk_bf16_f32 v72, v80, v81
	v_cvt_pk_bf16_f32 v73, v82, v83
	v_cvt_pk_bf16_f32 v74, v84, v85
	v_cvt_pk_bf16_f32 v75, v86, v87
	s_and_b64 vcc, exec, s[4:5]
	s_mov_b64 s[2:3], -1
	global_store_dwordx4 v[88:89], v[72:75], off sc1
	s_cbranch_vccnz .LBB0_227
	s_nop 0
	v_mul_f32_e32 v73, 0xbfb8aa3b, v64
	v_exp_f32_e32 v73, v73
	v_mul_f32_e32 v74, 0xbfb8aa3b, v69
	v_mul_f32_e32 v75, 0xbfb8aa3b, v65
	v_exp_f32_e32 v74, v74
	v_exp_f32_e32 v75, v75
	v_add_f32_e32 v73, 1.0, v73
	v_rcp_f32_e32 v76, v73
	v_add_f32_e32 v73, 1.0, v74
	v_add_f32_e32 v74, 1.0, v75
	v_mul_f32_e32 v75, 0xbfb8aa3b, v66
	v_mul_f32_e32 v78, 0xbfb8aa3b, v71
	v_exp_f32_e32 v75, v75
	v_exp_f32_e32 v78, v78
	v_mul_f32_e32 v72, 0xbfb8aa3b, v68
	v_rcp_f32_e32 v77, v74
	v_mul_f32_e32 v74, 0xbfb8aa3b, v70
	v_add_f32_e32 v79, 1.0, v75
	v_add_f32_e32 v75, 1.0, v78
	v_mul_f32_e32 v78, 0xbfb8aa3b, v67
	v_exp_f32_e32 v72, v72
	v_exp_f32_e32 v74, v74
	v_exp_f32_e32 v80, v78
	v_rcp_f32_e32 v78, v79
	v_add_f32_e32 v72, 1.0, v72
	v_add_f32_e32 v74, 1.0, v74
	v_add_f32_e32 v79, 1.0, v80
	v_rcp_f32_e32 v72, v72
	v_rcp_f32_e32 v73, v73
	v_rcp_f32_e32 v74, v74
	v_rcp_f32_e32 v75, v75
	v_rcp_f32_e32 v79, v79
	v_pk_mul_f32 v[72:73], v[68:69], v[72:73]
	v_pk_mul_f32 v[76:77], v[64:65], v[76:77]
	v_pk_mul_f32 v[74:75], v[70:71], v[74:75]
	v_pk_mul_f32 v[78:79], v[66:67], v[78:79]
	v_pk_mul_f32 v[74:75], v[74:75], s[6:7] op_sel_hi:[1,0]
	v_pk_mul_f32 v[72:73], v[72:73], s[6:7] op_sel_hi:[1,0]
	v_pk_mul_f32 v[78:79], v[78:79], s[6:7] op_sel_hi:[1,0]
	v_pk_mul_f32 v[76:77], v[76:77], s[6:7] op_sel_hi:[1,0]
	s_mov_b64 s[2:3], 0

.LBB0_229:
	v_cvt_pk_bf16_f32 v64, v72, v73
	v_cvt_pk_bf16_f32 v65, v74, v75
	s_nop 0
	v_cvt_pk_bf16_f32 v66, v76, v77
	v_cvt_pk_bf16_f32 v67, v78, v79
	s_and_b64 vcc, exec, s[4:5]
	s_mov_b64 s[2:3], -1
	global_store_dwordx4 v[88:89], v[64:67], off offset:256 sc1
	s_cbranch_vccnz .LBB0_231
	s_nop 0
	v_mul_f32_e32 v65, 0xbfb8aa3b, v56
	v_exp_f32_e32 v65, v65
	v_mul_f32_e32 v66, 0xbfb8aa3b, v61
	v_mul_f32_e32 v67, 0xbfb8aa3b, v57
	v_exp_f32_e32 v66, v66
	v_exp_f32_e32 v67, v67
	v_add_f32_e32 v65, 1.0, v65
	v_rcp_f32_e32 v68, v65
	v_add_f32_e32 v65, 1.0, v66
	v_add_f32_e32 v66, 1.0, v67
	v_mul_f32_e32 v67, 0xbfb8aa3b, v58
	v_mul_f32_e32 v70, 0xbfb8aa3b, v63
	v_exp_f32_e32 v67, v67
	v_exp_f32_e32 v70, v70
	v_mul_f32_e32 v64, 0xbfb8aa3b, v60
	v_rcp_f32_e32 v69, v66
	v_mul_f32_e32 v66, 0xbfb8aa3b, v62
	v_add_f32_e32 v71, 1.0, v67
	v_add_f32_e32 v67, 1.0, v70
	v_mul_f32_e32 v70, 0xbfb8aa3b, v59
	v_exp_f32_e32 v64, v64
	v_exp_f32_e32 v66, v66
	v_exp_f32_e32 v72, v70
	v_rcp_f32_e32 v70, v71
	v_add_f32_e32 v64, 1.0, v64
	v_add_f32_e32 v66, 1.0, v66
	v_add_f32_e32 v71, 1.0, v72
	v_rcp_f32_e32 v64, v64
	v_rcp_f32_e32 v65, v65
	v_rcp_f32_e32 v66, v66
	v_rcp_f32_e32 v67, v67
	v_rcp_f32_e32 v71, v71
	v_pk_mul_f32 v[64:65], v[60:61], v[64:65]
	v_pk_mul_f32 v[68:69], v[56:57], v[68:69]
	v_pk_mul_f32 v[66:67], v[62:63], v[66:67]
	v_pk_mul_f32 v[70:71], v[58:59], v[70:71]
	v_pk_mul_f32 v[66:67], v[66:67], s[6:7] op_sel_hi:[1,0]
	v_pk_mul_f32 v[64:65], v[64:65], s[6:7] op_sel_hi:[1,0]
	v_pk_mul_f32 v[70:71], v[70:71], s[6:7] op_sel_hi:[1,0]
	v_pk_mul_f32 v[68:69], v[68:69], s[6:7] op_sel_hi:[1,0]
	s_mov_b64 s[2:3], 0

.LBB0_233:
	v_lshlrev_b64 v[56:57], 10, v[162:163]
	v_lshl_add_u64 v[72:73], v[164:165], 0, v[56:57]
	v_add_co_u32_e32 v60, vcc, 0x20000, v72
	v_cvt_pk_bf16_f32 v56, v64, v65
	v_cvt_pk_bf16_f32 v57, v66, v67
	v_cvt_pk_bf16_f32 v58, v68, v69
	v_cvt_pk_bf16_f32 v59, v70, v71
	s_nop 1
	v_addc_co_u32_e32 v61, vcc, 0, v73, vcc
	s_and_b64 vcc, exec, s[4:5]
	s_mov_b64 s[2:3], -1
	global_store_dwordx4 v[60:61], v[56:59], off sc1
	s_cbranch_vccnz .LBB0_235
	s_nop 0
	v_mul_f32_e32 v57, 0xbfb8aa3b, v48
	v_exp_f32_e32 v57, v57
	v_mul_f32_e32 v58, 0xbfb8aa3b, v53
	v_mul_f32_e32 v59, 0xbfb8aa3b, v49
	v_exp_f32_e32 v58, v58
	v_exp_f32_e32 v59, v59
	v_add_f32_e32 v57, 1.0, v57
	v_rcp_f32_e32 v60, v57
	v_add_f32_e32 v57, 1.0, v58
	v_add_f32_e32 v58, 1.0, v59
	v_mul_f32_e32 v59, 0xbfb8aa3b, v50
	v_mul_f32_e32 v62, 0xbfb8aa3b, v55
	v_exp_f32_e32 v59, v59
	v_exp_f32_e32 v62, v62
	v_mul_f32_e32 v56, 0xbfb8aa3b, v52
	v_rcp_f32_e32 v61, v58
	v_mul_f32_e32 v58, 0xbfb8aa3b, v54
	v_add_f32_e32 v63, 1.0, v59
	v_add_f32_e32 v59, 1.0, v62
	v_mul_f32_e32 v62, 0xbfb8aa3b, v51
	v_exp_f32_e32 v56, v56
	v_exp_f32_e32 v58, v58
	v_exp_f32_e32 v64, v62
	v_rcp_f32_e32 v62, v63
	v_add_f32_e32 v56, 1.0, v56
	v_add_f32_e32 v58, 1.0, v58
	v_add_f32_e32 v63, 1.0, v64
	v_rcp_f32_e32 v56, v56
	v_rcp_f32_e32 v57, v57
	v_rcp_f32_e32 v58, v58
	v_rcp_f32_e32 v59, v59
	v_rcp_f32_e32 v63, v63
	v_pk_mul_f32 v[56:57], v[52:53], v[56:57]
	v_pk_mul_f32 v[60:61], v[48:49], v[60:61]
	v_pk_mul_f32 v[58:59], v[54:55], v[58:59]
	v_pk_mul_f32 v[62:63], v[50:51], v[62:63]
	v_pk_mul_f32 v[58:59], v[58:59], s[6:7] op_sel_hi:[1,0]
	v_pk_mul_f32 v[56:57], v[56:57], s[6:7] op_sel_hi:[1,0]
	v_pk_mul_f32 v[62:63], v[62:63], s[6:7] op_sel_hi:[1,0]
	v_pk_mul_f32 v[60:61], v[60:61], s[6:7] op_sel_hi:[1,0]
	s_mov_b64 s[2:3], 0

.LBB0_237:
	s_mov_b64 s[0:1], 0x20000
	v_lshl_add_u64 v[52:53], v[72:73], 0, s[0:1]
	v_cvt_pk_bf16_f32 v48, v56, v57
	v_cvt_pk_bf16_f32 v49, v58, v59
	v_cvt_pk_bf16_f32 v50, v60, v61
	v_cvt_pk_bf16_f32 v51, v62, v63
	s_and_b64 vcc, exec, s[4:5]
	s_mov_b64 s[2:3], -1
	global_store_dwordx4 v[52:53], v[48:51], off offset:256 sc1
	s_cbranch_vccnz .LBB0_239
	s_nop 0
	v_mul_f32_e32 v49, 0xbfb8aa3b, v40
	v_exp_f32_e32 v49, v49
	v_mul_f32_e32 v50, 0xbfb8aa3b, v45
	v_mul_f32_e32 v51, 0xbfb8aa3b, v41
	v_exp_f32_e32 v50, v50
	v_exp_f32_e32 v51, v51
	v_add_f32_e32 v49, 1.0, v49
	v_rcp_f32_e32 v52, v49
	v_add_f32_e32 v49, 1.0, v50
	v_add_f32_e32 v50, 1.0, v51
	v_mul_f32_e32 v51, 0xbfb8aa3b, v42
	v_mul_f32_e32 v54, 0xbfb8aa3b, v47
	v_exp_f32_e32 v51, v51
	v_exp_f32_e32 v54, v54
	v_mul_f32_e32 v48, 0xbfb8aa3b, v44
	v_rcp_f32_e32 v53, v50
	v_mul_f32_e32 v50, 0xbfb8aa3b, v46
	v_add_f32_e32 v55, 1.0, v51
	v_add_f32_e32 v51, 1.0, v54
	v_mul_f32_e32 v54, 0xbfb8aa3b, v43
	v_exp_f32_e32 v48, v48
	v_exp_f32_e32 v50, v50
	v_exp_f32_e32 v56, v54
	v_rcp_f32_e32 v54, v55
	v_add_f32_e32 v48, 1.0, v48
	v_add_f32_e32 v50, 1.0, v50
	v_add_f32_e32 v55, 1.0, v56
	v_rcp_f32_e32 v48, v48
	v_rcp_f32_e32 v49, v49
	v_rcp_f32_e32 v50, v50
	v_rcp_f32_e32 v51, v51
	v_rcp_f32_e32 v55, v55
	v_pk_mul_f32 v[48:49], v[44:45], v[48:49]
	v_pk_mul_f32 v[52:53], v[40:41], v[52:53]
	v_pk_mul_f32 v[50:51], v[46:47], v[50:51]
	v_pk_mul_f32 v[54:55], v[42:43], v[54:55]
	v_pk_mul_f32 v[50:51], v[50:51], s[6:7] op_sel_hi:[1,0]
	v_pk_mul_f32 v[48:49], v[48:49], s[6:7] op_sel_hi:[1,0]
	v_pk_mul_f32 v[54:55], v[54:55], s[6:7] op_sel_hi:[1,0]
	v_pk_mul_f32 v[52:53], v[52:53], s[6:7] op_sel_hi:[1,0]
	s_mov_b64 s[2:3], 0

.LBB0_241:
	v_lshlrev_b64 v[40:41], 10, v[162:163]
	v_lshl_add_u64 v[56:57], v[164:165], 0, v[40:41]
	v_add_co_u32_e32 v44, vcc, 0x24000, v56
	v_cvt_pk_bf16_f32 v40, v48, v49
	v_cvt_pk_bf16_f32 v41, v50, v51
	v_cvt_pk_bf16_f32 v42, v52, v53
	v_cvt_pk_bf16_f32 v43, v54, v55
	s_nop 1
	v_addc_co_u32_e32 v45, vcc, 0, v57, vcc
	s_and_b64 vcc, exec, s[4:5]
	s_mov_b64 s[2:3], -1
	global_store_dwordx4 v[44:45], v[40:43], off sc1
	s_cbranch_vccnz .LBB0_243
	s_nop 0
	v_mul_f32_e32 v41, 0xbfb8aa3b, v32
	v_exp_f32_e32 v41, v41
	v_mul_f32_e32 v42, 0xbfb8aa3b, v37
	v_mul_f32_e32 v43, 0xbfb8aa3b, v33
	v_exp_f32_e32 v42, v42
	v_exp_f32_e32 v43, v43
	v_add_f32_e32 v41, 1.0, v41
	v_rcp_f32_e32 v44, v41
	v_add_f32_e32 v41, 1.0, v42
	v_add_f32_e32 v42, 1.0, v43
	v_mul_f32_e32 v43, 0xbfb8aa3b, v34
	v_mul_f32_e32 v46, 0xbfb8aa3b, v39
	v_exp_f32_e32 v43, v43
	v_exp_f32_e32 v46, v46
	v_mul_f32_e32 v40, 0xbfb8aa3b, v36
	v_rcp_f32_e32 v45, v42
	v_mul_f32_e32 v42, 0xbfb8aa3b, v38
	v_add_f32_e32 v47, 1.0, v43
	v_add_f32_e32 v43, 1.0, v46
	v_mul_f32_e32 v46, 0xbfb8aa3b, v35
	v_exp_f32_e32 v40, v40
	v_exp_f32_e32 v42, v42
	v_exp_f32_e32 v48, v46
	v_rcp_f32_e32 v46, v47
	v_add_f32_e32 v40, 1.0, v40
	v_add_f32_e32 v42, 1.0, v42
	v_add_f32_e32 v47, 1.0, v48
	v_rcp_f32_e32 v40, v40
	v_rcp_f32_e32 v41, v41
	v_rcp_f32_e32 v42, v42
	v_rcp_f32_e32 v43, v43
	v_rcp_f32_e32 v47, v47
	v_pk_mul_f32 v[40:41], v[36:37], v[40:41]
	v_pk_mul_f32 v[44:45], v[32:33], v[44:45]
	v_pk_mul_f32 v[42:43], v[38:39], v[42:43]
	v_pk_mul_f32 v[46:47], v[34:35], v[46:47]
	v_pk_mul_f32 v[42:43], v[42:43], s[6:7] op_sel_hi:[1,0]
	v_pk_mul_f32 v[40:41], v[40:41], s[6:7] op_sel_hi:[1,0]
	v_pk_mul_f32 v[46:47], v[46:47], s[6:7] op_sel_hi:[1,0]
	v_pk_mul_f32 v[44:45], v[44:45], s[6:7] op_sel_hi:[1,0]
	s_mov_b64 s[2:3], 0

.LBB0_245:
	s_mov_b64 s[0:1], 0x24000
	v_lshl_add_u64 v[36:37], v[56:57], 0, s[0:1]
	v_cvt_pk_bf16_f32 v32, v40, v41
	v_cvt_pk_bf16_f32 v33, v42, v43
	v_cvt_pk_bf16_f32 v34, v44, v45
	v_cvt_pk_bf16_f32 v35, v46, v47
	s_and_b64 vcc, exec, s[4:5]
	s_mov_b64 s[2:3], -1
	global_store_dwordx4 v[36:37], v[32:35], off offset:256 sc1
	s_cbranch_vccnz .LBB0_247
	s_nop 0
	v_mul_f32_e32 v33, 0xbfb8aa3b, v24
	v_exp_f32_e32 v33, v33
	v_mul_f32_e32 v34, 0xbfb8aa3b, v29
	v_mul_f32_e32 v35, 0xbfb8aa3b, v25
	v_exp_f32_e32 v34, v34
	v_exp_f32_e32 v35, v35
	v_add_f32_e32 v33, 1.0, v33
	v_rcp_f32_e32 v36, v33
	v_add_f32_e32 v33, 1.0, v34
	v_add_f32_e32 v34, 1.0, v35
	v_mul_f32_e32 v35, 0xbfb8aa3b, v26
	v_mul_f32_e32 v38, 0xbfb8aa3b, v31
	v_exp_f32_e32 v35, v35
	v_exp_f32_e32 v38, v38
	v_mul_f32_e32 v32, 0xbfb8aa3b, v28
	v_rcp_f32_e32 v37, v34
	v_mul_f32_e32 v34, 0xbfb8aa3b, v30
	v_add_f32_e32 v39, 1.0, v35
	v_add_f32_e32 v35, 1.0, v38
	v_mul_f32_e32 v38, 0xbfb8aa3b, v27
	v_exp_f32_e32 v32, v32
	v_exp_f32_e32 v34, v34
	v_exp_f32_e32 v40, v38
	v_rcp_f32_e32 v38, v39
	v_add_f32_e32 v32, 1.0, v32
	v_add_f32_e32 v34, 1.0, v34
	v_add_f32_e32 v39, 1.0, v40
	v_rcp_f32_e32 v32, v32
	v_rcp_f32_e32 v33, v33
	v_rcp_f32_e32 v34, v34
	v_rcp_f32_e32 v35, v35
	v_rcp_f32_e32 v39, v39
	v_pk_mul_f32 v[32:33], v[28:29], v[32:33]
	v_pk_mul_f32 v[36:37], v[24:25], v[36:37]
	v_pk_mul_f32 v[34:35], v[30:31], v[34:35]
	v_pk_mul_f32 v[38:39], v[26:27], v[38:39]
	v_pk_mul_f32 v[34:35], v[34:35], s[6:7] op_sel_hi:[1,0]
	v_pk_mul_f32 v[32:33], v[32:33], s[6:7] op_sel_hi:[1,0]
	v_pk_mul_f32 v[38:39], v[38:39], s[6:7] op_sel_hi:[1,0]
	v_pk_mul_f32 v[36:37], v[36:37], s[6:7] op_sel_hi:[1,0]
	s_mov_b64 s[2:3], 0

.LBB0_249:
	v_lshlrev_b64 v[24:25], 10, v[162:163]
	v_lshl_add_u64 v[40:41], v[164:165], 0, v[24:25]
	v_add_co_u32_e32 v28, vcc, 0x28000, v40
	v_cvt_pk_bf16_f32 v24, v32, v33
	v_cvt_pk_bf16_f32 v25, v34, v35
	v_cvt_pk_bf16_f32 v26, v36, v37
	v_cvt_pk_bf16_f32 v27, v38, v39
	s_nop 1
	v_addc_co_u32_e32 v29, vcc, 0, v41, vcc
	s_and_b64 vcc, exec, s[4:5]
	s_mov_b64 s[2:3], -1
	global_store_dwordx4 v[28:29], v[24:27], off sc1
	s_cbranch_vccnz .LBB0_251
	s_nop 0
	v_mul_f32_e32 v25, 0xbfb8aa3b, v16
	v_exp_f32_e32 v25, v25
	v_mul_f32_e32 v26, 0xbfb8aa3b, v21
	v_mul_f32_e32 v27, 0xbfb8aa3b, v17
	v_exp_f32_e32 v26, v26
	v_exp_f32_e32 v27, v27
	v_add_f32_e32 v25, 1.0, v25
	v_rcp_f32_e32 v28, v25
	v_add_f32_e32 v25, 1.0, v26
	v_add_f32_e32 v26, 1.0, v27
	v_mul_f32_e32 v27, 0xbfb8aa3b, v18
	v_mul_f32_e32 v30, 0xbfb8aa3b, v23
	v_exp_f32_e32 v27, v27
	v_exp_f32_e32 v30, v30
	v_mul_f32_e32 v24, 0xbfb8aa3b, v20
	v_rcp_f32_e32 v29, v26
	v_mul_f32_e32 v26, 0xbfb8aa3b, v22
	v_add_f32_e32 v31, 1.0, v27
	v_add_f32_e32 v27, 1.0, v30
	v_mul_f32_e32 v30, 0xbfb8aa3b, v19
	v_exp_f32_e32 v24, v24
	v_exp_f32_e32 v26, v26
	v_exp_f32_e32 v32, v30
	v_rcp_f32_e32 v30, v31
	v_add_f32_e32 v24, 1.0, v24
	v_add_f32_e32 v26, 1.0, v26
	v_add_f32_e32 v31, 1.0, v32
	v_rcp_f32_e32 v24, v24
	v_rcp_f32_e32 v25, v25
	v_rcp_f32_e32 v26, v26
	v_rcp_f32_e32 v27, v27
	v_rcp_f32_e32 v31, v31
	v_pk_mul_f32 v[24:25], v[20:21], v[24:25]
	v_pk_mul_f32 v[28:29], v[16:17], v[28:29]
	v_pk_mul_f32 v[26:27], v[22:23], v[26:27]
	v_pk_mul_f32 v[30:31], v[18:19], v[30:31]
	v_pk_mul_f32 v[26:27], v[26:27], s[6:7] op_sel_hi:[1,0]
	v_pk_mul_f32 v[24:25], v[24:25], s[6:7] op_sel_hi:[1,0]
	v_pk_mul_f32 v[30:31], v[30:31], s[6:7] op_sel_hi:[1,0]
	v_pk_mul_f32 v[28:29], v[28:29], s[6:7] op_sel_hi:[1,0]
	s_mov_b64 s[2:3], 0

.LBB0_253:
	s_mov_b64 s[0:1], 0x28000
	v_lshl_add_u64 v[20:21], v[40:41], 0, s[0:1]
	v_cvt_pk_bf16_f32 v16, v24, v25
	v_cvt_pk_bf16_f32 v17, v26, v27
	v_cvt_pk_bf16_f32 v18, v28, v29
	v_cvt_pk_bf16_f32 v19, v30, v31
	s_and_b64 vcc, exec, s[4:5]
	s_mov_b64 s[2:3], -1
	global_store_dwordx4 v[20:21], v[16:19], off offset:256 sc1
	s_cbranch_vccnz .LBB0_255
	s_nop 0
	v_mul_f32_e32 v17, 0xbfb8aa3b, v8
	v_exp_f32_e32 v17, v17
	v_mul_f32_e32 v18, 0xbfb8aa3b, v13
	v_mul_f32_e32 v19, 0xbfb8aa3b, v9
	v_exp_f32_e32 v18, v18
	v_exp_f32_e32 v19, v19
	v_add_f32_e32 v17, 1.0, v17
	v_rcp_f32_e32 v20, v17
	v_add_f32_e32 v17, 1.0, v18
	v_add_f32_e32 v18, 1.0, v19
	v_mul_f32_e32 v19, 0xbfb8aa3b, v10
	v_mul_f32_e32 v22, 0xbfb8aa3b, v15
	v_exp_f32_e32 v19, v19
	v_exp_f32_e32 v22, v22
	v_mul_f32_e32 v16, 0xbfb8aa3b, v12
	v_rcp_f32_e32 v21, v18
	v_mul_f32_e32 v18, 0xbfb8aa3b, v14
	v_add_f32_e32 v23, 1.0, v19
	v_add_f32_e32 v19, 1.0, v22
	v_mul_f32_e32 v22, 0xbfb8aa3b, v11
	v_exp_f32_e32 v16, v16
	v_exp_f32_e32 v18, v18
	v_exp_f32_e32 v24, v22
	v_rcp_f32_e32 v22, v23
	v_add_f32_e32 v16, 1.0, v16
	v_add_f32_e32 v18, 1.0, v18
	v_add_f32_e32 v23, 1.0, v24
	v_rcp_f32_e32 v16, v16
	v_rcp_f32_e32 v17, v17
	v_rcp_f32_e32 v18, v18
	v_rcp_f32_e32 v19, v19
	v_rcp_f32_e32 v23, v23
	v_pk_mul_f32 v[16:17], v[12:13], v[16:17]
	v_pk_mul_f32 v[20:21], v[8:9], v[20:21]
	v_pk_mul_f32 v[18:19], v[14:15], v[18:19]
	v_pk_mul_f32 v[22:23], v[10:11], v[22:23]
	v_pk_mul_f32 v[18:19], v[18:19], s[6:7] op_sel_hi:[1,0]
	v_pk_mul_f32 v[16:17], v[16:17], s[6:7] op_sel_hi:[1,0]
	v_pk_mul_f32 v[22:23], v[22:23], s[6:7] op_sel_hi:[1,0]
	v_pk_mul_f32 v[20:21], v[20:21], s[6:7] op_sel_hi:[1,0]
	s_mov_b64 s[2:3], 0

.LBB0_257:
	v_lshlrev_b64 v[8:9], 10, v[162:163]
	v_lshl_add_u64 v[24:25], v[164:165], 0, v[8:9]
	v_add_co_u32_e32 v12, vcc, 0x2c000, v24
	v_cvt_pk_bf16_f32 v8, v16, v17
	v_cvt_pk_bf16_f32 v9, v18, v19
	v_cvt_pk_bf16_f32 v10, v20, v21
	v_cvt_pk_bf16_f32 v11, v22, v23
	s_nop 1
	v_addc_co_u32_e32 v13, vcc, 0, v25, vcc
	s_and_b64 vcc, exec, s[4:5]
	s_mov_b64 s[2:3], -1
	global_store_dwordx4 v[12:13], v[8:11], off sc1
	s_cbranch_vccnz .LBB0_259
	s_nop 0
	v_mul_f32_e32 v9, 0xbfb8aa3b, v0
	v_exp_f32_e32 v9, v9
	v_mul_f32_e32 v10, 0xbfb8aa3b, v5
	v_mul_f32_e32 v11, 0xbfb8aa3b, v1
	v_exp_f32_e32 v10, v10
	v_exp_f32_e32 v11, v11
	v_add_f32_e32 v9, 1.0, v9
	v_rcp_f32_e32 v12, v9
	v_add_f32_e32 v9, 1.0, v10
	v_add_f32_e32 v10, 1.0, v11
	v_mul_f32_e32 v11, 0xbfb8aa3b, v2
	v_mul_f32_e32 v14, 0xbfb8aa3b, v7
	v_exp_f32_e32 v11, v11
	v_exp_f32_e32 v14, v14
	v_mul_f32_e32 v8, 0xbfb8aa3b, v4
	v_rcp_f32_e32 v13, v10
	v_mul_f32_e32 v10, 0xbfb8aa3b, v6
	v_add_f32_e32 v15, 1.0, v11
	v_add_f32_e32 v11, 1.0, v14
	v_mul_f32_e32 v14, 0xbfb8aa3b, v3
	v_exp_f32_e32 v8, v8
	v_exp_f32_e32 v10, v10
	v_exp_f32_e32 v16, v14
	v_rcp_f32_e32 v14, v15
	v_add_f32_e32 v8, 1.0, v8
	v_add_f32_e32 v10, 1.0, v10
	v_add_f32_e32 v15, 1.0, v16
	v_rcp_f32_e32 v8, v8
	v_rcp_f32_e32 v9, v9
	v_rcp_f32_e32 v10, v10
	v_rcp_f32_e32 v11, v11
	v_rcp_f32_e32 v15, v15
	v_pk_mul_f32 v[8:9], v[4:5], v[8:9]
	v_pk_mul_f32 v[12:13], v[0:1], v[12:13]
	v_pk_mul_f32 v[10:11], v[6:7], v[10:11]
	v_pk_mul_f32 v[14:15], v[2:3], v[14:15]
	v_pk_mul_f32 v[10:11], v[10:11], s[6:7] op_sel_hi:[1,0]
	v_pk_mul_f32 v[8:9], v[8:9], s[6:7] op_sel_hi:[1,0]
	v_pk_mul_f32 v[14:15], v[14:15], s[6:7] op_sel_hi:[1,0]
	v_pk_mul_f32 v[12:13], v[12:13], s[6:7] op_sel_hi:[1,0]
	s_mov_b64 s[2:3], 0
